# baseline (speedup 1.0000x reference)
; __device__ __forceinline__ void wkv_phase(const WkvT& W, unsigned char* lds) {
;     ...
;             if (c + 1 < 256) wkv_issue(W, raw, rowbase, cbase, q, c + 1, tid);
;             {
;                 const float* pp = sP + bo + jj * 12;
;                 const float* pv = sV + bi * 512 + il;
;                 f32x4 nA = *(const f32x4*)pp, nB = *(const f32x4*)(pp + 4); f32x2 nr = *(const f32x2*)(pp + 8); float nv = pv[0];
;                 float yk0 = 0.f, yk1 = 0.f, ep = 0.f;
;                 const bool oddrow = (lane & 16) != 0;
; #pragma unroll
;                 for (int t = 0; t < 32; ++t) {
;                     const f32x2 a2 = {nA[0], nA[1]}, w2 = {nA[2], nA[3]}, b2 = {nB[0], nB[1]}, k2 = {nB[2], nB[3]}, r2 = nr; const float v = nv;
;                     if (t + 1 < 32) { nA = *(const f32x4*)(pp + (t + 1) * 384); nB = *(const f32x4*)(pp + (t + 1) * 384 + 4); nr = *(const f32x2*)(pp + (t + 1) * 384 + 8); nv = pv[(t + 1) * 16]; }
;                     float S0 = S.x, S1 = S.y;
;                     float d = S0 * a2.x; d = __builtin_fmaf(S1, a2.y, d);
;                     float t0 = S0 * w2.x; t0 = __builtin_fmaf(v, k2.x, t0); asm volatile("" : "+v"(t0));
;                     float t1 = S1 * w2.y; t1 = __builtin_fmaf(v, k2.y, t1); asm volatile("" : "+v"(t1));
;                     float yprev; const float sa = wkv_reduce(d, ep, yprev);
;                     S0 = __builtin_fmaf(sa, b2.x, t0); asm volatile("" : "+v"(S0));
;                     S1 = __builtin_fmaf(sa, b2.y, t1); asm volatile("" : "+v"(S1));
;                     ep = S0 * r2.x; ep = __builtin_fmaf(S1, r2.y, ep);
;                     S.x = S0; S.y = S1;
.Lwkv4_b1_entry:
	s_bitcmp1_b32 s99, 8
	s_cbranch_scc1 .Lwkv4_b1_skip
	ds_read_b128 v[190:193], v182
	ds_read_b128 v[194:197], v182 offset:16
	ds_read_b64 v[228:229], v182 offset:32
	ds_read_b128 v[198:201], v183
	ds_read_b128 v[202:205], v183 offset:16
	ds_read_b64 v[230:231], v183 offset:32
	ds_read2_b32 v[240:241], v186 offset0:0 offset1:16
	ds_read_b128 v[206:209], v182 offset:1536
	ds_read_b128 v[210:213], v182 offset:1552
	ds_read_b64 v[232:233], v182 offset:1568
	ds_read_b128 v[214:217], v183 offset:1536
	ds_read_b128 v[218:221], v183 offset:1552
	ds_read_b64 v[234:235], v183 offset:1568
	s_waitcnt lgkmcnt(6)
	v_pk_mul_f32 v[150:151], v[142:143], v[190:191]
	v_pk_fma_f32 v[150:151], v[144:145], v[198:199], v[150:151]
	v_pk_mul_f32 v[146:147], v[142:143], v[192:193]
	v_add_f32_e32 v154, v150, v151
	v_pk_mul_f32 v[148:149], v[144:145], v[200:201]
	v_pk_fma_f32 v[146:147], v[240:241], v[196:197], v[146:147] op_sel:[0,0,0] op_sel_hi:[0,1,1]
	v_add_f32_dpp v154, v154, v154 quad_perm:[1,0,3,2] row_mask:0xf bank_mask:0xf bound_ctrl:1
	v_pk_fma_f32 v[148:149], v[240:241], v[204:205], v[148:149] op_sel:[0,0,0] op_sel_hi:[0,1,1]
	s_nop 0
	v_add_f32_dpp v154, v154, v154 quad_perm:[2,3,0,1] row_mask:0xf bank_mask:0xf bound_ctrl:1
	ds_read_b128 v[126:129], v182 offset:3072
	ds_read_b128 v[130:133], v182 offset:3088
	v_add_f32_dpp v154, v154, v154 row_half_mirror row_mask:0xf bank_mask:0xf bound_ctrl:1
	ds_read_b64 v[236:237], v182 offset:3104
	ds_read_b128 v[134:137], v183 offset:3072
	v_add_f32_dpp v154, v154, v154 row_mirror row_mask:0xf bank_mask:0xf bound_ctrl:1
	v_pk_fma_f32 v[146:147], v[154:155], v[194:195], v[146:147] op_sel_hi:[0,1,1]
	v_pk_fma_f32 v[148:149], v[154:155], v[202:203], v[148:149] op_sel_hi:[0,1,1]
	ds_read_b128 v[222:225], v183 offset:3088
	ds_read_b64 v[238:239], v183 offset:3104
	ds_read2_b32 v[242:243], v186 offset0:32 offset1:48
	s_waitcnt lgkmcnt(7)
	v_pk_mul_f32 v[150:151], v[146:147], v[206:207]
	v_pk_fma_f32 v[150:151], v[148:149], v[214:215], v[150:151]
	v_pk_mul_f32 v[152:153], v[146:147], v[228:229]
	v_add_f32_e32 v154, v150, v151
	v_pk_fma_f32 v[152:153], v[148:149], v[230:231], v[152:153]
	v_pk_mul_f32 v[142:143], v[146:147], v[208:209]
	v_add_f32_dpp v154, v154, v154 quad_perm:[1,0,3,2] row_mask:0xf bank_mask:0xf bound_ctrl:1
	v_pk_mul_f32 v[144:145], v[148:149], v[216:217]
	v_add_f32_e32 v156, v152, v153
	v_add_f32_dpp v154, v154, v154 quad_perm:[2,3,0,1] row_mask:0xf bank_mask:0xf bound_ctrl:1
	v_pk_fma_f32 v[142:143], v[240:241], v[212:213], v[142:143] op_sel:[1,0,0] op_sel_hi:[1,1,1]
	v_pk_fma_f32 v[144:145], v[240:241], v[220:221], v[144:145] op_sel:[1,0,0] op_sel_hi:[1,1,1]
	v_add_f32_dpp v154, v154, v154 row_half_mirror row_mask:0xf bank_mask:0xf bound_ctrl:1
	ds_read_b128 v[190:193], v182 offset:4608
	ds_read_b128 v[194:197], v182 offset:4624
	v_add_f32_dpp v154, v154, v154 row_mirror row_mask:0xf bank_mask:0xf bound_ctrl:1
	ds_read_b64 v[228:229], v182 offset:4640
	v_pk_fma_f32 v[142:143], v[154:155], v[210:211], v[142:143] op_sel_hi:[0,1,1]
	v_pk_fma_f32 v[144:145], v[154:155], v[218:219], v[144:145] op_sel_hi:[0,1,1]
	ds_read_b128 v[198:201], v183 offset:4608
	ds_read_b128 v[202:205], v183 offset:4624
	ds_read_b64 v[230:231], v183 offset:4640
	s_waitcnt lgkmcnt(6)
	v_pk_mul_f32 v[150:151], v[142:143], v[126:127]
	v_pk_fma_f32 v[150:151], v[144:145], v[134:135], v[150:151]
	v_pk_mul_f32 v[152:153], v[142:143], v[232:233]
	v_add_f32_e32 v154, v150, v151
	v_pk_fma_f32 v[152:153], v[144:145], v[234:235], v[152:153]
	v_pk_mul_f32 v[146:147], v[142:143], v[128:129]
	v_add_f32_dpp v154, v154, v154 quad_perm:[1,0,3,2] row_mask:0xf bank_mask:0xf bound_ctrl:1
	v_pk_mul_f32 v[148:149], v[144:145], v[136:137]
	v_add_f32_e32 v157, v152, v153
	v_add_f32_dpp v154, v154, v154 quad_perm:[2,3,0,1] row_mask:0xf bank_mask:0xf bound_ctrl:1
	v_pk_fma_f32 v[146:147], v[242:243], v[132:133], v[146:147] op_sel:[0,0,0] op_sel_hi:[0,1,1]
	v_pk_fma_f32 v[148:149], v[242:243], v[224:225], v[148:149] op_sel:[0,0,0] op_sel_hi:[0,1,1]
	v_add_f32_dpp v154, v154, v154 row_half_mirror row_mask:0xf bank_mask:0xf bound_ctrl:1
	ds_read_b128 v[206:209], v182 offset:6144
	ds_read_b128 v[210:213], v182 offset:6160
	v_add_f32_dpp v154, v154, v154 row_mirror row_mask:0xf bank_mask:0xf bound_ctrl:1
	ds_read_b64 v[232:233], v182 offset:6176
	ds_read_b128 v[214:217], v183 offset:6144
	v_pk_fma_f32 v[146:147], v[154:155], v[130:131], v[146:147] op_sel_hi:[0,1,1]
	v_pk_fma_f32 v[148:149], v[154:155], v[222:223], v[148:149] op_sel_hi:[0,1,1]
	ds_read_b128 v[218:221], v183 offset:6160
	ds_read_b64 v[234:235], v183 offset:6176
	ds_read2_b32 v[240:241], v186 offset0:64 offset1:80
	s_waitcnt lgkmcnt(7)
	v_pk_mul_f32 v[150:151], v[146:147], v[190:191]
	v_pk_fma_f32 v[150:151], v[148:149], v[198:199], v[150:151]
	v_pk_mul_f32 v[152:153], v[146:147], v[236:237]
	v_add_f32_e32 v154, v150, v151
	v_pk_fma_f32 v[152:153], v[148:149], v[238:239], v[152:153]
	v_pk_mul_f32 v[142:143], v[146:147], v[192:193]
	v_add_f32_dpp v154, v154, v154 quad_perm:[1,0,3,2] row_mask:0xf bank_mask:0xf bound_ctrl:1
	v_pk_mul_f32 v[144:145], v[148:149], v[200:201]
	v_add_f32_e32 v158, v152, v153
	v_add_f32_dpp v154, v154, v154 quad_perm:[2,3,0,1] row_mask:0xf bank_mask:0xf bound_ctrl:1
	v_pk_fma_f32 v[142:143], v[242:243], v[196:197], v[142:143] op_sel:[1,0,0] op_sel_hi:[1,1,1]
	v_pk_fma_f32 v[144:145], v[242:243], v[204:205], v[144:145] op_sel:[1,0,0] op_sel_hi:[1,1,1]
	v_add_f32_dpp v154, v154, v154 row_half_mirror row_mask:0xf bank_mask:0xf bound_ctrl:1
	ds_read_b128 v[126:129], v182 offset:7680
	ds_read_b128 v[130:133], v182 offset:7696
	v_add_f32_dpp v154, v154, v154 row_mirror row_mask:0xf bank_mask:0xf bound_ctrl:1
	ds_read_b64 v[236:237], v182 offset:7712
	v_pk_fma_f32 v[142:143], v[154:155], v[194:195], v[142:143] op_sel_hi:[0,1,1]
	v_pk_fma_f32 v[144:145], v[154:155], v[202:203], v[144:145] op_sel_hi:[0,1,1]
	ds_read_b128 v[134:137], v183 offset:7680
	ds_read_b128 v[222:225], v183 offset:7696
	ds_read_b64 v[238:239], v183 offset:7712
	s_waitcnt lgkmcnt(6)
; __device__ __forceinline__ void wkv_phase(const WkvT& W, unsigned char* lds) {
;     ...
;                 const float* pp = sP + bo + jj * 12;
;                 const float* pv = sV + bi * 512 + il;
;                 f32x4 nA = *(const f32x4*)pp, nB = *(const f32x4*)(pp + 4); f32x2 nr = *(const f32x2*)(pp + 8); float nv = pv[0];
;                 float yk0 = 0.f, yk1 = 0.f, ep = 0.f;
;                 const bool oddrow = (lane & 16) != 0;
; #pragma unroll
;                 for (int t = 0; t < 32; ++t) {
;                     const f32x2 a2 = {nA[0], nA[1]}, w2 = {nA[2], nA[3]}, b2 = {nB[0], nB[1]}, k2 = {nB[2], nB[3]}, r2 = nr; const float v = nv;
;                     if (t + 1 < 32) { nA = *(const f32x4*)(pp + (t + 1) * 384); nB = *(const f32x4*)(pp + (t + 1) * 384 + 4); nr = *(const f32x2*)(pp + (t + 1) * 384 + 8); nv = pv[(t + 1) * 16]; }
;                     float S0 = S.x, S1 = S.y;
;                     float d = S0 * a2.x; d = __builtin_fmaf(S1, a2.y, d);
;                     float t0 = S0 * w2.x; t0 = __builtin_fmaf(v, k2.x, t0); asm volatile("" : "+v"(t0));
;                     float t1 = S1 * w2.y; t1 = __builtin_fmaf(v, k2.y, t1); asm volatile("" : "+v"(t1));
;                     float yprev; const float sa = wkv_reduce(d, ep, yprev);
;                     S0 = __builtin_fmaf(sa, b2.x, t0); asm volatile("" : "+v"(S0));
;                     S1 = __builtin_fmaf(sa, b2.y, t1); asm volatile("" : "+v"(S1));
;                     ep = S0 * r2.x; ep = __builtin_fmaf(S1, r2.y, ep);
;                     S.x = S0; S.y = S1;
	v_pk_mul_f32 v[150:151], v[142:143], v[206:207]
	v_pk_fma_f32 v[150:151], v[144:145], v[214:215], v[150:151]
	v_pk_mul_f32 v[152:153], v[142:143], v[228:229]
	v_add_f32_e32 v154, v150, v151
	v_pk_fma_f32 v[152:153], v[144:145], v[230:231], v[152:153]
	v_pk_mul_f32 v[146:147], v[142:143], v[208:209]
	v_add_f32_dpp v154, v154, v154 quad_perm:[1,0,3,2] row_mask:0xf bank_mask:0xf bound_ctrl:1
	v_pk_mul_f32 v[148:149], v[144:145], v[216:217]
	v_add_f32_e32 v159, v152, v153
	v_add_f32_dpp v154, v154, v154 quad_perm:[2,3,0,1] row_mask:0xf bank_mask:0xf bound_ctrl:1
	v_pk_fma_f32 v[146:147], v[240:241], v[212:213], v[146:147] op_sel:[0,0,0] op_sel_hi:[0,1,1]
	v_pk_fma_f32 v[148:149], v[240:241], v[220:221], v[148:149] op_sel:[0,0,0] op_sel_hi:[0,1,1]
	v_add_f32_dpp v154, v154, v154 row_half_mirror row_mask:0xf bank_mask:0xf bound_ctrl:1
	ds_read_b128 v[190:193], v182 offset:9216
	ds_read_b128 v[194:197], v182 offset:9232
	v_add_f32_dpp v154, v154, v154 row_mirror row_mask:0xf bank_mask:0xf bound_ctrl:1
	ds_read_b64 v[228:229], v182 offset:9248
	ds_read_b128 v[198:201], v183 offset:9216
	v_pk_fma_f32 v[146:147], v[154:155], v[210:211], v[146:147] op_sel_hi:[0,1,1]
	v_pk_fma_f32 v[148:149], v[154:155], v[218:219], v[148:149] op_sel_hi:[0,1,1]
	ds_read_b128 v[202:205], v183 offset:9232
	ds_read_b64 v[230:231], v183 offset:9248
	ds_read2_b32 v[242:243], v186 offset0:96 offset1:112
	s_waitcnt lgkmcnt(7)
	v_pk_mul_f32 v[150:151], v[146:147], v[126:127]
	v_pk_fma_f32 v[150:151], v[148:149], v[134:135], v[150:151]
	v_pk_mul_f32 v[152:153], v[146:147], v[232:233]
	v_add_f32_e32 v154, v150, v151
	v_pk_fma_f32 v[152:153], v[148:149], v[234:235], v[152:153]
	v_pk_mul_f32 v[142:143], v[146:147], v[128:129]
	v_add_f32_dpp v154, v154, v154 quad_perm:[1,0,3,2] row_mask:0xf bank_mask:0xf bound_ctrl:1
	v_pk_mul_f32 v[144:145], v[148:149], v[136:137]
	v_add_f32_e32 v160, v152, v153
	v_add_f32_dpp v154, v154, v154 quad_perm:[2,3,0,1] row_mask:0xf bank_mask:0xf bound_ctrl:1
	v_pk_fma_f32 v[142:143], v[240:241], v[132:133], v[142:143] op_sel:[1,0,0] op_sel_hi:[1,1,1]
	v_pk_fma_f32 v[144:145], v[240:241], v[224:225], v[144:145] op_sel:[1,0,0] op_sel_hi:[1,1,1]
	v_add_f32_dpp v154, v154, v154 row_half_mirror row_mask:0xf bank_mask:0xf bound_ctrl:1
	ds_read_b128 v[206:209], v182 offset:10752
	ds_read_b128 v[210:213], v182 offset:10768
	v_add_f32_dpp v154, v154, v154 row_mirror row_mask:0xf bank_mask:0xf bound_ctrl:1
	ds_read_b64 v[232:233], v182 offset:10784
	v_pk_fma_f32 v[142:143], v[154:155], v[130:131], v[142:143] op_sel_hi:[0,1,1]
	v_pk_fma_f32 v[144:145], v[154:155], v[222:223], v[144:145] op_sel_hi:[0,1,1]
	ds_read_b128 v[214:217], v183 offset:10752
	ds_read_b128 v[218:221], v183 offset:10768
	ds_read_b64 v[234:235], v183 offset:10784
	s_waitcnt lgkmcnt(6)
	v_pk_mul_f32 v[150:151], v[142:143], v[190:191]
	v_pk_fma_f32 v[150:151], v[144:145], v[198:199], v[150:151]
	v_pk_mul_f32 v[152:153], v[142:143], v[236:237]
	v_add_f32_e32 v154, v150, v151
	v_pk_fma_f32 v[152:153], v[144:145], v[238:239], v[152:153]
	v_pk_mul_f32 v[146:147], v[142:143], v[192:193]
	v_add_f32_dpp v154, v154, v154 quad_perm:[1,0,3,2] row_mask:0xf bank_mask:0xf bound_ctrl:1
	v_pk_mul_f32 v[148:149], v[144:145], v[200:201]
	v_add_f32_e32 v161, v152, v153
	v_add_f32_dpp v154, v154, v154 quad_perm:[2,3,0,1] row_mask:0xf bank_mask:0xf bound_ctrl:1
	v_pk_fma_f32 v[146:147], v[242:243], v[196:197], v[146:147] op_sel:[0,0,0] op_sel_hi:[0,1,1]
	v_pk_fma_f32 v[148:149], v[242:243], v[204:205], v[148:149] op_sel:[0,0,0] op_sel_hi:[0,1,1]
	v_add_f32_dpp v154, v154, v154 row_half_mirror row_mask:0xf bank_mask:0xf bound_ctrl:1
	ds_read_b128 v[126:129], v182 offset:12288
	ds_read_b128 v[130:133], v182 offset:12304
	v_add_f32_dpp v154, v154, v154 row_mirror row_mask:0xf bank_mask:0xf bound_ctrl:1
	ds_read_b64 v[236:237], v182 offset:12320
	ds_read_b128 v[134:137], v183 offset:12288
	v_pk_fma_f32 v[146:147], v[154:155], v[194:195], v[146:147] op_sel_hi:[0,1,1]
	v_pk_fma_f32 v[148:149], v[154:155], v[202:203], v[148:149] op_sel_hi:[0,1,1]
	ds_read_b128 v[222:225], v183 offset:12304
	ds_read_b64 v[238:239], v183 offset:12320
	ds_read2_b32 v[240:241], v186 offset0:128 offset1:144
	s_waitcnt lgkmcnt(7)
	v_pk_mul_f32 v[150:151], v[146:147], v[206:207]
	v_pk_fma_f32 v[150:151], v[148:149], v[214:215], v[150:151]
	v_pk_mul_f32 v[152:153], v[146:147], v[228:229]
	v_add_f32_e32 v154, v150, v151
	v_pk_fma_f32 v[152:153], v[148:149], v[230:231], v[152:153]
	v_pk_mul_f32 v[142:143], v[146:147], v[208:209]
	v_add_f32_dpp v154, v154, v154 quad_perm:[1,0,3,2] row_mask:0xf bank_mask:0xf bound_ctrl:1
	v_pk_mul_f32 v[144:145], v[148:149], v[216:217]
	v_add_f32_e32 v162, v152, v153
	v_add_f32_dpp v154, v154, v154 quad_perm:[2,3,0,1] row_mask:0xf bank_mask:0xf bound_ctrl:1
	v_pk_fma_f32 v[142:143], v[242:243], v[212:213], v[142:143] op_sel:[1,0,0] op_sel_hi:[1,1,1]
	v_pk_fma_f32 v[144:145], v[242:243], v[220:221], v[144:145] op_sel:[1,0,0] op_sel_hi:[1,1,1]
	v_add_f32_dpp v154, v154, v154 row_half_mirror row_mask:0xf bank_mask:0xf bound_ctrl:1
	ds_read_b128 v[190:193], v182 offset:13824
	ds_read_b128 v[194:197], v182 offset:13840
	v_add_f32_dpp v154, v154, v154 row_mirror row_mask:0xf bank_mask:0xf bound_ctrl:1
	ds_read_b64 v[228:229], v182 offset:13856
	v_pk_fma_f32 v[142:143], v[154:155], v[210:211], v[142:143] op_sel_hi:[0,1,1]
	v_pk_fma_f32 v[144:145], v[154:155], v[218:219], v[144:145] op_sel_hi:[0,1,1]
	ds_read_b128 v[198:201], v183 offset:13824
	ds_read_b128 v[202:205], v183 offset:13840
	ds_read_b64 v[230:231], v183 offset:13856
	s_waitcnt lgkmcnt(6)
; __device__ __forceinline__ void wkv_phase(const WkvT& W, unsigned char* lds) {
;     ...
;                 const float* pp = sP + bo + jj * 12;
;                 const float* pv = sV + bi * 512 + il;
;                 f32x4 nA = *(const f32x4*)pp, nB = *(const f32x4*)(pp + 4); f32x2 nr = *(const f32x2*)(pp + 8); float nv = pv[0];
;                 float yk0 = 0.f, yk1 = 0.f, ep = 0.f;
;                 const bool oddrow = (lane & 16) != 0;
; #pragma unroll
;                 for (int t = 0; t < 32; ++t) {
;                     const f32x2 a2 = {nA[0], nA[1]}, w2 = {nA[2], nA[3]}, b2 = {nB[0], nB[1]}, k2 = {nB[2], nB[3]}, r2 = nr; const float v = nv;
;                     if (t + 1 < 32) { nA = *(const f32x4*)(pp + (t + 1) * 384); nB = *(const f32x4*)(pp + (t + 1) * 384 + 4); nr = *(const f32x2*)(pp + (t + 1) * 384 + 8); nv = pv[(t + 1) * 16]; }
;                     float S0 = S.x, S1 = S.y;
;                     float d = S0 * a2.x; d = __builtin_fmaf(S1, a2.y, d);
;                     float t0 = S0 * w2.x; t0 = __builtin_fmaf(v, k2.x, t0); asm volatile("" : "+v"(t0));
;                     float t1 = S1 * w2.y; t1 = __builtin_fmaf(v, k2.y, t1); asm volatile("" : "+v"(t1));
;                     float yprev; const float sa = wkv_reduce(d, ep, yprev);
;                     S0 = __builtin_fmaf(sa, b2.x, t0); asm volatile("" : "+v"(S0));
;                     S1 = __builtin_fmaf(sa, b2.y, t1); asm volatile("" : "+v"(S1));
;                     ep = S0 * r2.x; ep = __builtin_fmaf(S1, r2.y, ep);
;                     S.x = S0; S.y = S1;
	v_pk_mul_f32 v[150:151], v[142:143], v[126:127]
	v_pk_fma_f32 v[150:151], v[144:145], v[134:135], v[150:151]
	v_pk_mul_f32 v[152:153], v[142:143], v[232:233]
	v_add_f32_e32 v154, v150, v151
	v_pk_fma_f32 v[152:153], v[144:145], v[234:235], v[152:153]
	v_pk_mul_f32 v[146:147], v[142:143], v[128:129]
	v_add_f32_dpp v154, v154, v154 quad_perm:[1,0,3,2] row_mask:0xf bank_mask:0xf bound_ctrl:1
	v_pk_mul_f32 v[148:149], v[144:145], v[136:137]
	v_add_f32_e32 v163, v152, v153
	v_add_f32_dpp v154, v154, v154 quad_perm:[2,3,0,1] row_mask:0xf bank_mask:0xf bound_ctrl:1
	v_pk_fma_f32 v[146:147], v[240:241], v[132:133], v[146:147] op_sel:[0,0,0] op_sel_hi:[0,1,1]
	v_pk_fma_f32 v[148:149], v[240:241], v[224:225], v[148:149] op_sel:[0,0,0] op_sel_hi:[0,1,1]
	v_add_f32_dpp v154, v154, v154 row_half_mirror row_mask:0xf bank_mask:0xf bound_ctrl:1
	ds_read_b128 v[206:209], v182 offset:15360
	ds_read_b128 v[210:213], v182 offset:15376
	v_add_f32_dpp v154, v154, v154 row_mirror row_mask:0xf bank_mask:0xf bound_ctrl:1
	ds_read_b64 v[232:233], v182 offset:15392
	ds_read_b128 v[214:217], v183 offset:15360
	v_pk_fma_f32 v[146:147], v[154:155], v[130:131], v[146:147] op_sel_hi:[0,1,1]
	v_pk_fma_f32 v[148:149], v[154:155], v[222:223], v[148:149] op_sel_hi:[0,1,1]
	ds_read_b128 v[218:221], v183 offset:15376
	ds_read_b64 v[234:235], v183 offset:15392
	ds_read2_b32 v[242:243], v186 offset0:160 offset1:176
	s_waitcnt lgkmcnt(7)
	v_pk_mul_f32 v[150:151], v[146:147], v[190:191]
	v_pk_fma_f32 v[150:151], v[148:149], v[198:199], v[150:151]
	v_pk_mul_f32 v[152:153], v[146:147], v[236:237]
	v_add_f32_e32 v154, v150, v151
	v_pk_fma_f32 v[152:153], v[148:149], v[238:239], v[152:153]
	v_pk_mul_f32 v[142:143], v[146:147], v[192:193]
	v_add_f32_dpp v154, v154, v154 quad_perm:[1,0,3,2] row_mask:0xf bank_mask:0xf bound_ctrl:1
	v_pk_mul_f32 v[144:145], v[148:149], v[200:201]
	v_add_f32_e32 v164, v152, v153
	v_add_f32_dpp v154, v154, v154 quad_perm:[2,3,0,1] row_mask:0xf bank_mask:0xf bound_ctrl:1
	v_pk_fma_f32 v[142:143], v[240:241], v[196:197], v[142:143] op_sel:[1,0,0] op_sel_hi:[1,1,1]
	v_pk_fma_f32 v[144:145], v[240:241], v[204:205], v[144:145] op_sel:[1,0,0] op_sel_hi:[1,1,1]
	v_add_f32_dpp v154, v154, v154 row_half_mirror row_mask:0xf bank_mask:0xf bound_ctrl:1
	ds_read_b128 v[126:129], v182 offset:16896
	ds_read_b128 v[130:133], v182 offset:16912
	v_add_f32_dpp v154, v154, v154 row_mirror row_mask:0xf bank_mask:0xf bound_ctrl:1
	ds_read_b64 v[236:237], v182 offset:16928
	v_pk_fma_f32 v[142:143], v[154:155], v[194:195], v[142:143] op_sel_hi:[0,1,1]
	v_pk_fma_f32 v[144:145], v[154:155], v[202:203], v[144:145] op_sel_hi:[0,1,1]
	ds_read_b128 v[134:137], v183 offset:16896
	ds_read_b128 v[222:225], v183 offset:16912
	ds_read_b64 v[238:239], v183 offset:16928
	s_waitcnt lgkmcnt(6)
	v_pk_mul_f32 v[150:151], v[142:143], v[206:207]
	v_pk_fma_f32 v[150:151], v[144:145], v[214:215], v[150:151]
	v_pk_mul_f32 v[152:153], v[142:143], v[228:229]
	v_add_f32_e32 v154, v150, v151
	v_pk_fma_f32 v[152:153], v[144:145], v[230:231], v[152:153]
	v_pk_mul_f32 v[146:147], v[142:143], v[208:209]
	v_add_f32_dpp v154, v154, v154 quad_perm:[1,0,3,2] row_mask:0xf bank_mask:0xf bound_ctrl:1
	v_pk_mul_f32 v[148:149], v[144:145], v[216:217]
	v_add_f32_e32 v165, v152, v153
	v_add_f32_dpp v154, v154, v154 quad_perm:[2,3,0,1] row_mask:0xf bank_mask:0xf bound_ctrl:1
	v_pk_fma_f32 v[146:147], v[242:243], v[212:213], v[146:147] op_sel:[0,0,0] op_sel_hi:[0,1,1]
	v_pk_fma_f32 v[148:149], v[242:243], v[220:221], v[148:149] op_sel:[0,0,0] op_sel_hi:[0,1,1]
	v_add_f32_dpp v154, v154, v154 row_half_mirror row_mask:0xf bank_mask:0xf bound_ctrl:1
	ds_read_b128 v[190:193], v182 offset:18432
	ds_read_b128 v[194:197], v182 offset:18448
	v_add_f32_dpp v154, v154, v154 row_mirror row_mask:0xf bank_mask:0xf bound_ctrl:1
	ds_read_b64 v[228:229], v182 offset:18464
	ds_read_b128 v[198:201], v183 offset:18432
	v_pk_fma_f32 v[146:147], v[154:155], v[210:211], v[146:147] op_sel_hi:[0,1,1]
	v_pk_fma_f32 v[148:149], v[154:155], v[218:219], v[148:149] op_sel_hi:[0,1,1]
	ds_read_b128 v[202:205], v183 offset:18448
	ds_read_b64 v[230:231], v183 offset:18464
	ds_read2_b32 v[240:241], v186 offset0:192 offset1:208
	s_waitcnt lgkmcnt(7)
	v_pk_mul_f32 v[150:151], v[146:147], v[126:127]
	v_pk_fma_f32 v[150:151], v[148:149], v[134:135], v[150:151]
	v_pk_mul_f32 v[152:153], v[146:147], v[232:233]
	v_add_f32_e32 v154, v150, v151
	v_pk_fma_f32 v[152:153], v[148:149], v[234:235], v[152:153]
	v_pk_mul_f32 v[142:143], v[146:147], v[128:129]
	v_add_f32_dpp v154, v154, v154 quad_perm:[1,0,3,2] row_mask:0xf bank_mask:0xf bound_ctrl:1
	v_pk_mul_f32 v[144:145], v[148:149], v[136:137]
	v_add_f32_e32 v166, v152, v153
	v_add_f32_dpp v154, v154, v154 quad_perm:[2,3,0,1] row_mask:0xf bank_mask:0xf bound_ctrl:1
	v_pk_fma_f32 v[142:143], v[242:243], v[132:133], v[142:143] op_sel:[1,0,0] op_sel_hi:[1,1,1]
	v_pk_fma_f32 v[144:145], v[242:243], v[224:225], v[144:145] op_sel:[1,0,0] op_sel_hi:[1,1,1]
	v_add_f32_dpp v154, v154, v154 row_half_mirror row_mask:0xf bank_mask:0xf bound_ctrl:1
	ds_read_b128 v[206:209], v182 offset:19968
	ds_read_b128 v[210:213], v182 offset:19984
	v_add_f32_dpp v154, v154, v154 row_mirror row_mask:0xf bank_mask:0xf bound_ctrl:1
	ds_read_b64 v[232:233], v182 offset:20000
	v_pk_fma_f32 v[142:143], v[154:155], v[130:131], v[142:143] op_sel_hi:[0,1,1]
	v_pk_fma_f32 v[144:145], v[154:155], v[222:223], v[144:145] op_sel_hi:[0,1,1]
	ds_read_b128 v[214:217], v183 offset:19968
	ds_read_b128 v[218:221], v183 offset:19984
	ds_read_b64 v[234:235], v183 offset:20000
	s_waitcnt lgkmcnt(6)
; __device__ __forceinline__ void wkv_phase(const WkvT& W, unsigned char* lds) {
;     ...
;                 const float* pp = sP + bo + jj * 12;
;                 const float* pv = sV + bi * 512 + il;
;                 f32x4 nA = *(const f32x4*)pp, nB = *(const f32x4*)(pp + 4); f32x2 nr = *(const f32x2*)(pp + 8); float nv = pv[0];
;                 float yk0 = 0.f, yk1 = 0.f, ep = 0.f;
;                 const bool oddrow = (lane & 16) != 0;
; #pragma unroll
;                 for (int t = 0; t < 32; ++t) {
;                     const f32x2 a2 = {nA[0], nA[1]}, w2 = {nA[2], nA[3]}, b2 = {nB[0], nB[1]}, k2 = {nB[2], nB[3]}, r2 = nr; const float v = nv;
;                     if (t + 1 < 32) { nA = *(const f32x4*)(pp + (t + 1) * 384); nB = *(const f32x4*)(pp + (t + 1) * 384 + 4); nr = *(const f32x2*)(pp + (t + 1) * 384 + 8); nv = pv[(t + 1) * 16]; }
;                     float S0 = S.x, S1 = S.y;
;                     float d = S0 * a2.x; d = __builtin_fmaf(S1, a2.y, d);
;                     float t0 = S0 * w2.x; t0 = __builtin_fmaf(v, k2.x, t0); asm volatile("" : "+v"(t0));
;                     float t1 = S1 * w2.y; t1 = __builtin_fmaf(v, k2.y, t1); asm volatile("" : "+v"(t1));
;                     float yprev; const float sa = wkv_reduce(d, ep, yprev);
;                     S0 = __builtin_fmaf(sa, b2.x, t0); asm volatile("" : "+v"(S0));
;                     S1 = __builtin_fmaf(sa, b2.y, t1); asm volatile("" : "+v"(S1));
;                     ep = S0 * r2.x; ep = __builtin_fmaf(S1, r2.y, ep);
;                     S.x = S0; S.y = S1;
	v_pk_mul_f32 v[150:151], v[142:143], v[190:191]
	v_pk_fma_f32 v[150:151], v[144:145], v[198:199], v[150:151]
	v_pk_mul_f32 v[152:153], v[142:143], v[236:237]
	v_add_f32_e32 v154, v150, v151
	v_pk_fma_f32 v[152:153], v[144:145], v[238:239], v[152:153]
	v_pk_mul_f32 v[146:147], v[142:143], v[192:193]
	v_add_f32_dpp v154, v154, v154 quad_perm:[1,0,3,2] row_mask:0xf bank_mask:0xf bound_ctrl:1
	v_pk_mul_f32 v[148:149], v[144:145], v[200:201]
	v_add_f32_e32 v167, v152, v153
	v_add_f32_dpp v154, v154, v154 quad_perm:[2,3,0,1] row_mask:0xf bank_mask:0xf bound_ctrl:1
	v_pk_fma_f32 v[146:147], v[240:241], v[196:197], v[146:147] op_sel:[0,0,0] op_sel_hi:[0,1,1]
	v_pk_fma_f32 v[148:149], v[240:241], v[204:205], v[148:149] op_sel:[0,0,0] op_sel_hi:[0,1,1]
	v_add_f32_dpp v154, v154, v154 row_half_mirror row_mask:0xf bank_mask:0xf bound_ctrl:1
	ds_read_b128 v[126:129], v182 offset:21504
	ds_read_b128 v[130:133], v182 offset:21520
	v_add_f32_dpp v154, v154, v154 row_mirror row_mask:0xf bank_mask:0xf bound_ctrl:1
	ds_read_b64 v[236:237], v182 offset:21536
	ds_read_b128 v[134:137], v183 offset:21504
	v_pk_fma_f32 v[146:147], v[154:155], v[194:195], v[146:147] op_sel_hi:[0,1,1]
	v_pk_fma_f32 v[148:149], v[154:155], v[202:203], v[148:149] op_sel_hi:[0,1,1]
	ds_read_b128 v[222:225], v183 offset:21520
	ds_read_b64 v[238:239], v183 offset:21536
	ds_read2_b32 v[242:243], v186 offset0:224 offset1:240
	s_waitcnt lgkmcnt(7)
	v_pk_mul_f32 v[150:151], v[146:147], v[206:207]
	v_pk_fma_f32 v[150:151], v[148:149], v[214:215], v[150:151]
	v_pk_mul_f32 v[152:153], v[146:147], v[228:229]
	v_add_f32_e32 v154, v150, v151
	v_pk_fma_f32 v[152:153], v[148:149], v[230:231], v[152:153]
	v_pk_mul_f32 v[142:143], v[146:147], v[208:209]
	v_add_f32_dpp v154, v154, v154 quad_perm:[1,0,3,2] row_mask:0xf bank_mask:0xf bound_ctrl:1
	v_pk_mul_f32 v[144:145], v[148:149], v[216:217]
	v_add_f32_e32 v168, v152, v153
	v_add_f32_dpp v154, v154, v154 quad_perm:[2,3,0,1] row_mask:0xf bank_mask:0xf bound_ctrl:1
	v_pk_fma_f32 v[142:143], v[240:241], v[212:213], v[142:143] op_sel:[1,0,0] op_sel_hi:[1,1,1]
	v_pk_fma_f32 v[144:145], v[240:241], v[220:221], v[144:145] op_sel:[1,0,0] op_sel_hi:[1,1,1]
	v_add_f32_dpp v154, v154, v154 row_half_mirror row_mask:0xf bank_mask:0xf bound_ctrl:1
	ds_read_b128 v[190:193], v182 offset:23040
	ds_read_b128 v[194:197], v182 offset:23056
	v_add_f32_dpp v154, v154, v154 row_mirror row_mask:0xf bank_mask:0xf bound_ctrl:1
	ds_read_b64 v[228:229], v182 offset:23072
	v_pk_fma_f32 v[142:143], v[154:155], v[210:211], v[142:143] op_sel_hi:[0,1,1]
	v_pk_fma_f32 v[144:145], v[154:155], v[218:219], v[144:145] op_sel_hi:[0,1,1]
	ds_read_b128 v[198:201], v183 offset:23040
	ds_read_b128 v[202:205], v183 offset:23056
	ds_read_b64 v[230:231], v183 offset:23072
	s_waitcnt lgkmcnt(6)
	v_pk_mul_f32 v[150:151], v[142:143], v[126:127]
	v_pk_fma_f32 v[150:151], v[144:145], v[134:135], v[150:151]
	v_pk_mul_f32 v[152:153], v[142:143], v[232:233]
	v_add_f32_e32 v154, v150, v151
	v_pk_fma_f32 v[152:153], v[144:145], v[234:235], v[152:153]
	v_pk_mul_f32 v[146:147], v[142:143], v[128:129]
	v_add_f32_dpp v154, v154, v154 quad_perm:[1,0,3,2] row_mask:0xf bank_mask:0xf bound_ctrl:1
	v_pk_mul_f32 v[148:149], v[144:145], v[136:137]
	v_add_f32_e32 v169, v152, v153
	v_add_f32_dpp v154, v154, v154 quad_perm:[2,3,0,1] row_mask:0xf bank_mask:0xf bound_ctrl:1
	v_pk_fma_f32 v[146:147], v[242:243], v[132:133], v[146:147] op_sel:[0,0,0] op_sel_hi:[0,1,1]
	v_pk_fma_f32 v[148:149], v[242:243], v[224:225], v[148:149] op_sel:[0,0,0] op_sel_hi:[0,1,1]
	v_add_f32_dpp v154, v154, v154 row_half_mirror row_mask:0xf bank_mask:0xf bound_ctrl:1
	ds_read_b128 v[206:209], v182 offset:24576
	ds_read_b128 v[210:213], v182 offset:24592
	v_add_f32_dpp v154, v154, v154 row_mirror row_mask:0xf bank_mask:0xf bound_ctrl:1
	ds_read_b64 v[232:233], v182 offset:24608
	ds_read_b128 v[214:217], v183 offset:24576
	v_pk_fma_f32 v[146:147], v[154:155], v[130:131], v[146:147] op_sel_hi:[0,1,1]
	v_pk_fma_f32 v[148:149], v[154:155], v[222:223], v[148:149] op_sel_hi:[0,1,1]
	ds_read_b128 v[218:221], v183 offset:24592
	ds_read_b64 v[234:235], v183 offset:24608
	ds_read2_b32 v[240:241], v189 offset0:0 offset1:16
	s_waitcnt lgkmcnt(7)
	v_pk_mul_f32 v[150:151], v[146:147], v[190:191]
	v_pk_fma_f32 v[150:151], v[148:149], v[198:199], v[150:151]
	v_pk_mul_f32 v[152:153], v[146:147], v[236:237]
	v_add_f32_e32 v154, v150, v151
	v_pk_fma_f32 v[152:153], v[148:149], v[238:239], v[152:153]
	v_pk_mul_f32 v[142:143], v[146:147], v[192:193]
	v_add_f32_dpp v154, v154, v154 quad_perm:[1,0,3,2] row_mask:0xf bank_mask:0xf bound_ctrl:1
	v_pk_mul_f32 v[144:145], v[148:149], v[200:201]
	v_add_f32_e32 v170, v152, v153
	v_add_f32_dpp v154, v154, v154 quad_perm:[2,3,0,1] row_mask:0xf bank_mask:0xf bound_ctrl:1
	v_pk_fma_f32 v[142:143], v[242:243], v[196:197], v[142:143] op_sel:[1,0,0] op_sel_hi:[1,1,1]
	v_pk_fma_f32 v[144:145], v[242:243], v[204:205], v[144:145] op_sel:[1,0,0] op_sel_hi:[1,1,1]
	v_add_f32_dpp v154, v154, v154 row_half_mirror row_mask:0xf bank_mask:0xf bound_ctrl:1
	ds_read_b128 v[126:129], v182 offset:26112
	ds_read_b128 v[130:133], v182 offset:26128
	v_add_f32_dpp v154, v154, v154 row_mirror row_mask:0xf bank_mask:0xf bound_ctrl:1
	ds_read_b64 v[236:237], v182 offset:26144
	v_pk_fma_f32 v[142:143], v[154:155], v[194:195], v[142:143] op_sel_hi:[0,1,1]
	v_pk_fma_f32 v[144:145], v[154:155], v[202:203], v[144:145] op_sel_hi:[0,1,1]
	ds_read_b128 v[134:137], v183 offset:26112
	ds_read_b128 v[222:225], v183 offset:26128
	ds_read_b64 v[238:239], v183 offset:26144
	s_waitcnt lgkmcnt(6)
; __device__ __forceinline__ void wkv_phase(const WkvT& W, unsigned char* lds) {
;     ...
;                 const float* pp = sP + bo + jj * 12;
;                 const float* pv = sV + bi * 512 + il;
;                 f32x4 nA = *(const f32x4*)pp, nB = *(const f32x4*)(pp + 4); f32x2 nr = *(const f32x2*)(pp + 8); float nv = pv[0];
;                 float yk0 = 0.f, yk1 = 0.f, ep = 0.f;
;                 const bool oddrow = (lane & 16) != 0;
; #pragma unroll
;                 for (int t = 0; t < 32; ++t) {
;                     const f32x2 a2 = {nA[0], nA[1]}, w2 = {nA[2], nA[3]}, b2 = {nB[0], nB[1]}, k2 = {nB[2], nB[3]}, r2 = nr; const float v = nv;
;                     if (t + 1 < 32) { nA = *(const f32x4*)(pp + (t + 1) * 384); nB = *(const f32x4*)(pp + (t + 1) * 384 + 4); nr = *(const f32x2*)(pp + (t + 1) * 384 + 8); nv = pv[(t + 1) * 16]; }
;                     float S0 = S.x, S1 = S.y;
;                     float d = S0 * a2.x; d = __builtin_fmaf(S1, a2.y, d);
;                     float t0 = S0 * w2.x; t0 = __builtin_fmaf(v, k2.x, t0); asm volatile("" : "+v"(t0));
;                     float t1 = S1 * w2.y; t1 = __builtin_fmaf(v, k2.y, t1); asm volatile("" : "+v"(t1));
;                     float yprev; const float sa = wkv_reduce(d, ep, yprev);
;                     S0 = __builtin_fmaf(sa, b2.x, t0); asm volatile("" : "+v"(S0));
;                     S1 = __builtin_fmaf(sa, b2.y, t1); asm volatile("" : "+v"(S1));
;                     ep = S0 * r2.x; ep = __builtin_fmaf(S1, r2.y, ep);
;                     S.x = S0; S.y = S1;
;                     if (t >= 1) { const bool hit = oddrow && ((lane & 15) == ((t - 1) & 15)); if (t <= 16) yk0 = hit ? yprev : yk0; else yk1 = hit ? yprev : yk1; }
;                 }
;                 { float ylast; (void)wkv_reduce(0.f, ep, ylast); yk1 = (oddrow && (lane & 15) == 15) ? ylast : yk1; }
;                 if (oddrow) { sY[bi * 512 + (lane & 15) * 16 + il] = yk0; sY[bi * 512 + (16 + (lane & 15)) * 16 + il] = yk1; }
	v_pk_mul_f32 v[150:151], v[142:143], v[206:207]
	v_pk_fma_f32 v[150:151], v[144:145], v[214:215], v[150:151]
	v_pk_mul_f32 v[152:153], v[142:143], v[228:229]
	v_add_f32_e32 v154, v150, v151
	v_pk_fma_f32 v[152:153], v[144:145], v[230:231], v[152:153]
	v_pk_mul_f32 v[146:147], v[142:143], v[208:209]
	v_add_f32_dpp v154, v154, v154 quad_perm:[1,0,3,2] row_mask:0xf bank_mask:0xf bound_ctrl:1
	v_pk_mul_f32 v[148:149], v[144:145], v[216:217]
	v_add_f32_e32 v171, v152, v153
	v_add_f32_dpp v154, v154, v154 quad_perm:[2,3,0,1] row_mask:0xf bank_mask:0xf bound_ctrl:1
	v_pk_fma_f32 v[146:147], v[240:241], v[212:213], v[146:147] op_sel:[0,0,0] op_sel_hi:[0,1,1]
	v_pk_fma_f32 v[148:149], v[240:241], v[220:221], v[148:149] op_sel:[0,0,0] op_sel_hi:[0,1,1]
	v_add_f32_dpp v154, v154, v154 row_half_mirror row_mask:0xf bank_mask:0xf bound_ctrl:1
	ds_read_b128 v[190:193], v182 offset:27648
	ds_read_b128 v[194:197], v182 offset:27664
	v_add_f32_dpp v154, v154, v154 row_mirror row_mask:0xf bank_mask:0xf bound_ctrl:1
	ds_read_b64 v[228:229], v182 offset:27680
	ds_read_b128 v[198:201], v183 offset:27648
	v_pk_fma_f32 v[146:147], v[154:155], v[210:211], v[146:147] op_sel_hi:[0,1,1]
	v_pk_fma_f32 v[148:149], v[154:155], v[218:219], v[148:149] op_sel_hi:[0,1,1]
	ds_read_b128 v[202:205], v183 offset:27664
	ds_read_b64 v[230:231], v183 offset:27680
	ds_read2_b32 v[242:243], v189 offset0:32 offset1:48
	s_waitcnt lgkmcnt(7)
	v_add_f32_dpp v172, v156, v156 row_ror:8 row_mask:0xf bank_mask:0x3
	v_add_f32_dpp v173, v157, v157 row_ror:8 row_mask:0xf bank_mask:0x3
	v_add_f32_dpp v174, v158, v158 row_ror:8 row_mask:0xf bank_mask:0x3
	v_add_f32_dpp v175, v159, v159 row_ror:8 row_mask:0xf bank_mask:0x3
	v_add_f32_dpp v176, v160, v160 row_ror:8 row_mask:0xf bank_mask:0x3
	v_add_f32_dpp v177, v161, v161 row_ror:8 row_mask:0xf bank_mask:0x3
	v_add_f32_dpp v178, v162, v162 row_ror:8 row_mask:0xf bank_mask:0x3
	v_add_f32_dpp v179, v163, v163 row_ror:8 row_mask:0xf bank_mask:0x3
	v_add_f32_dpp v172, v164, v164 row_ror:8 row_mask:0xf bank_mask:0xc
	v_add_f32_dpp v173, v165, v165 row_ror:8 row_mask:0xf bank_mask:0xc
	v_add_f32_dpp v174, v166, v166 row_ror:8 row_mask:0xf bank_mask:0xc
	v_add_f32_dpp v175, v167, v167 row_ror:8 row_mask:0xf bank_mask:0xc
	v_add_f32_dpp v176, v168, v168 row_ror:8 row_mask:0xf bank_mask:0xc
	v_add_f32_dpp v177, v169, v169 row_ror:8 row_mask:0xf bank_mask:0xc
	v_add_f32_dpp v178, v170, v170 row_ror:8 row_mask:0xf bank_mask:0xc
	v_add_f32_dpp v179, v171, v171 row_ror:8 row_mask:0xf bank_mask:0xc
	v_add_f32_dpp v156, v172, v172 row_half_mirror row_mask:0xf bank_mask:0x5
	v_add_f32_dpp v157, v173, v173 row_half_mirror row_mask:0xf bank_mask:0x5
	v_add_f32_dpp v158, v174, v174 row_half_mirror row_mask:0xf bank_mask:0x5
	v_add_f32_dpp v159, v175, v175 row_half_mirror row_mask:0xf bank_mask:0x5
	v_add_f32_dpp v156, v176, v176 row_half_mirror row_mask:0xf bank_mask:0xa
	v_add_f32_dpp v157, v177, v177 row_half_mirror row_mask:0xf bank_mask:0xa
	v_add_f32_dpp v158, v178, v178 row_half_mirror row_mask:0xf bank_mask:0xa
	v_add_f32_dpp v159, v179, v179 row_half_mirror row_mask:0xf bank_mask:0xa
	v_cndmask_b32_e64 v178, v156, v158, s[14:15]
	v_cndmask_b32_e64 v176, v158, v156, s[14:15]
	v_cndmask_b32_e64 v179, v157, v159, s[14:15]
	v_cndmask_b32_e64 v177, v159, v157, s[14:15]
	s_nop 1
	v_add_f32_dpp v172, v176, v178 quad_perm:[2,3,0,1] row_mask:0xf bank_mask:0xf
	v_add_f32_dpp v173, v177, v179 quad_perm:[2,3,0,1] row_mask:0xf bank_mask:0xf
	v_cndmask_b32_e64 v176, v173, v172, s[16:17]
	v_cndmask_b32_e64 v178, v172, v173, s[16:17]
	s_nop 1
	v_add_f32_dpp v180, v176, v178 quad_perm:[1,0,3,2] row_mask:0xf bank_mask:0xf
	v_pk_mul_f32 v[150:151], v[146:147], v[126:127]
	v_pk_fma_f32 v[150:151], v[148:149], v[134:135], v[150:151]
	v_pk_mul_f32 v[152:153], v[146:147], v[232:233]
	v_add_f32_e32 v154, v150, v151
	v_pk_fma_f32 v[152:153], v[148:149], v[234:235], v[152:153]
	v_pk_mul_f32 v[142:143], v[146:147], v[128:129]
	v_add_f32_dpp v154, v154, v154 quad_perm:[1,0,3,2] row_mask:0xf bank_mask:0xf bound_ctrl:1
	v_pk_mul_f32 v[144:145], v[148:149], v[136:137]
	v_add_f32_e32 v156, v152, v153
	v_add_f32_dpp v154, v154, v154 quad_perm:[2,3,0,1] row_mask:0xf bank_mask:0xf bound_ctrl:1
	v_pk_fma_f32 v[142:143], v[240:241], v[132:133], v[142:143] op_sel:[1,0,0] op_sel_hi:[1,1,1]
	v_pk_fma_f32 v[144:145], v[240:241], v[224:225], v[144:145] op_sel:[1,0,0] op_sel_hi:[1,1,1]
	v_add_f32_dpp v154, v154, v154 row_half_mirror row_mask:0xf bank_mask:0xf bound_ctrl:1
	ds_read_b128 v[206:209], v182 offset:29184
	ds_read_b128 v[210:213], v182 offset:29200
	v_add_f32_dpp v154, v154, v154 row_mirror row_mask:0xf bank_mask:0xf bound_ctrl:1
	ds_read_b64 v[232:233], v182 offset:29216
	v_pk_fma_f32 v[142:143], v[154:155], v[130:131], v[142:143] op_sel_hi:[0,1,1]
	v_pk_fma_f32 v[144:145], v[154:155], v[222:223], v[144:145] op_sel_hi:[0,1,1]
	ds_read_b128 v[214:217], v183 offset:29184
	ds_read_b128 v[218:221], v183 offset:29200
	ds_read_b64 v[234:235], v183 offset:29216
	s_waitcnt lgkmcnt(6)
; __device__ __forceinline__ void wkv_phase(const WkvT& W, unsigned char* lds) {
;     ...
;                 const float* pp = sP + bo + jj * 12;
;                 const float* pv = sV + bi * 512 + il;
;                 f32x4 nA = *(const f32x4*)pp, nB = *(const f32x4*)(pp + 4); f32x2 nr = *(const f32x2*)(pp + 8); float nv = pv[0];
;                 float yk0 = 0.f, yk1 = 0.f, ep = 0.f;
;                 const bool oddrow = (lane & 16) != 0;
; #pragma unroll
;                 for (int t = 0; t < 32; ++t) {
;                     const f32x2 a2 = {nA[0], nA[1]}, w2 = {nA[2], nA[3]}, b2 = {nB[0], nB[1]}, k2 = {nB[2], nB[3]}, r2 = nr; const float v = nv;
;                     if (t + 1 < 32) { nA = *(const f32x4*)(pp + (t + 1) * 384); nB = *(const f32x4*)(pp + (t + 1) * 384 + 4); nr = *(const f32x2*)(pp + (t + 1) * 384 + 8); nv = pv[(t + 1) * 16]; }
;                     float S0 = S.x, S1 = S.y;
;                     float d = S0 * a2.x; d = __builtin_fmaf(S1, a2.y, d);
;                     float t0 = S0 * w2.x; t0 = __builtin_fmaf(v, k2.x, t0); asm volatile("" : "+v"(t0));
;                     float t1 = S1 * w2.y; t1 = __builtin_fmaf(v, k2.y, t1); asm volatile("" : "+v"(t1));
;                     float yprev; const float sa = wkv_reduce(d, ep, yprev);
;                     S0 = __builtin_fmaf(sa, b2.x, t0); asm volatile("" : "+v"(S0));
;                     S1 = __builtin_fmaf(sa, b2.y, t1); asm volatile("" : "+v"(S1));
;                     ep = S0 * r2.x; ep = __builtin_fmaf(S1, r2.y, ep);
;                     S.x = S0; S.y = S1;
	v_pk_mul_f32 v[150:151], v[142:143], v[190:191]
	v_pk_fma_f32 v[150:151], v[144:145], v[198:199], v[150:151]
	v_pk_mul_f32 v[152:153], v[142:143], v[236:237]
	v_add_f32_e32 v154, v150, v151
	v_pk_fma_f32 v[152:153], v[144:145], v[238:239], v[152:153]
	v_pk_mul_f32 v[146:147], v[142:143], v[192:193]
	v_add_f32_dpp v154, v154, v154 quad_perm:[1,0,3,2] row_mask:0xf bank_mask:0xf bound_ctrl:1
	v_pk_mul_f32 v[148:149], v[144:145], v[200:201]
	v_add_f32_e32 v157, v152, v153
	v_add_f32_dpp v154, v154, v154 quad_perm:[2,3,0,1] row_mask:0xf bank_mask:0xf bound_ctrl:1
	v_pk_fma_f32 v[146:147], v[242:243], v[196:197], v[146:147] op_sel:[0,0,0] op_sel_hi:[0,1,1]
	v_pk_fma_f32 v[148:149], v[242:243], v[204:205], v[148:149] op_sel:[0,0,0] op_sel_hi:[0,1,1]
	v_add_f32_dpp v154, v154, v154 row_half_mirror row_mask:0xf bank_mask:0xf bound_ctrl:1
	ds_read_b128 v[126:129], v182 offset:30720
	ds_read_b128 v[130:133], v182 offset:30736
	v_add_f32_dpp v154, v154, v154 row_mirror row_mask:0xf bank_mask:0xf bound_ctrl:1
	ds_read_b64 v[236:237], v182 offset:30752
	ds_read_b128 v[134:137], v183 offset:30720
	v_pk_fma_f32 v[146:147], v[154:155], v[194:195], v[146:147] op_sel_hi:[0,1,1]
	v_pk_fma_f32 v[148:149], v[154:155], v[202:203], v[148:149] op_sel_hi:[0,1,1]
	ds_read_b128 v[222:225], v183 offset:30736
	ds_read_b64 v[238:239], v183 offset:30752
	ds_read2_b32 v[240:241], v189 offset0:64 offset1:80
	s_waitcnt lgkmcnt(7)
	v_pk_mul_f32 v[150:151], v[146:147], v[206:207]
	v_pk_fma_f32 v[150:151], v[148:149], v[214:215], v[150:151]
	v_pk_mul_f32 v[152:153], v[146:147], v[228:229]
	v_add_f32_e32 v154, v150, v151
	v_pk_fma_f32 v[152:153], v[148:149], v[230:231], v[152:153]
	v_pk_mul_f32 v[142:143], v[146:147], v[208:209]
	v_add_f32_dpp v154, v154, v154 quad_perm:[1,0,3,2] row_mask:0xf bank_mask:0xf bound_ctrl:1
	v_pk_mul_f32 v[144:145], v[148:149], v[216:217]
	v_add_f32_e32 v158, v152, v153
	v_add_f32_dpp v154, v154, v154 quad_perm:[2,3,0,1] row_mask:0xf bank_mask:0xf bound_ctrl:1
	v_pk_fma_f32 v[142:143], v[242:243], v[212:213], v[142:143] op_sel:[1,0,0] op_sel_hi:[1,1,1]
	v_pk_fma_f32 v[144:145], v[242:243], v[220:221], v[144:145] op_sel:[1,0,0] op_sel_hi:[1,1,1]
	v_add_f32_dpp v154, v154, v154 row_half_mirror row_mask:0xf bank_mask:0xf bound_ctrl:1
	ds_read_b128 v[190:193], v182 offset:32256
	ds_read_b128 v[194:197], v182 offset:32272
	v_add_f32_dpp v154, v154, v154 row_mirror row_mask:0xf bank_mask:0xf bound_ctrl:1
	ds_read_b64 v[228:229], v182 offset:32288
	v_pk_fma_f32 v[142:143], v[154:155], v[210:211], v[142:143] op_sel_hi:[0,1,1]
	v_pk_fma_f32 v[144:145], v[154:155], v[218:219], v[144:145] op_sel_hi:[0,1,1]
	ds_read_b128 v[198:201], v183 offset:32256
	ds_read_b128 v[202:205], v183 offset:32272
	ds_read_b64 v[230:231], v183 offset:32288
	s_waitcnt lgkmcnt(6)
	v_pk_mul_f32 v[150:151], v[142:143], v[126:127]
	v_pk_fma_f32 v[150:151], v[144:145], v[134:135], v[150:151]
	v_pk_mul_f32 v[152:153], v[142:143], v[232:233]
	v_add_f32_e32 v154, v150, v151
	v_pk_fma_f32 v[152:153], v[144:145], v[234:235], v[152:153]
	v_pk_mul_f32 v[146:147], v[142:143], v[128:129]
	v_add_f32_dpp v154, v154, v154 quad_perm:[1,0,3,2] row_mask:0xf bank_mask:0xf bound_ctrl:1
	v_pk_mul_f32 v[148:149], v[144:145], v[136:137]
	v_add_f32_e32 v159, v152, v153
	v_add_f32_dpp v154, v154, v154 quad_perm:[2,3,0,1] row_mask:0xf bank_mask:0xf bound_ctrl:1
	v_pk_fma_f32 v[146:147], v[240:241], v[132:133], v[146:147] op_sel:[0,0,0] op_sel_hi:[0,1,1]
	v_pk_fma_f32 v[148:149], v[240:241], v[224:225], v[148:149] op_sel:[0,0,0] op_sel_hi:[0,1,1]
	v_add_f32_dpp v154, v154, v154 row_half_mirror row_mask:0xf bank_mask:0xf bound_ctrl:1
	ds_read_b128 v[206:209], v182 offset:33792
	ds_read_b128 v[210:213], v182 offset:33808
	v_add_f32_dpp v154, v154, v154 row_mirror row_mask:0xf bank_mask:0xf bound_ctrl:1
	ds_read_b64 v[232:233], v182 offset:33824
	ds_read_b128 v[214:217], v183 offset:33792
	v_pk_fma_f32 v[146:147], v[154:155], v[130:131], v[146:147] op_sel_hi:[0,1,1]
	v_pk_fma_f32 v[148:149], v[154:155], v[222:223], v[148:149] op_sel_hi:[0,1,1]
	ds_read_b128 v[218:221], v183 offset:33808
	ds_read_b64 v[234:235], v183 offset:33824
	ds_read2_b32 v[242:243], v189 offset0:96 offset1:112
	s_waitcnt lgkmcnt(7)
	v_pk_mul_f32 v[150:151], v[146:147], v[190:191]
	v_pk_fma_f32 v[150:151], v[148:149], v[198:199], v[150:151]
	v_pk_mul_f32 v[152:153], v[146:147], v[236:237]
	v_add_f32_e32 v154, v150, v151
	v_pk_fma_f32 v[152:153], v[148:149], v[238:239], v[152:153]
	v_pk_mul_f32 v[142:143], v[146:147], v[192:193]
	v_add_f32_dpp v154, v154, v154 quad_perm:[1,0,3,2] row_mask:0xf bank_mask:0xf bound_ctrl:1
	v_pk_mul_f32 v[144:145], v[148:149], v[200:201]
	v_add_f32_e32 v160, v152, v153
	v_add_f32_dpp v154, v154, v154 quad_perm:[2,3,0,1] row_mask:0xf bank_mask:0xf bound_ctrl:1
	v_pk_fma_f32 v[142:143], v[240:241], v[196:197], v[142:143] op_sel:[1,0,0] op_sel_hi:[1,1,1]
	v_pk_fma_f32 v[144:145], v[240:241], v[204:205], v[144:145] op_sel:[1,0,0] op_sel_hi:[1,1,1]
	v_add_f32_dpp v154, v154, v154 row_half_mirror row_mask:0xf bank_mask:0xf bound_ctrl:1
	ds_read_b128 v[126:129], v182 offset:35328
	ds_read_b128 v[130:133], v182 offset:35344
	v_add_f32_dpp v154, v154, v154 row_mirror row_mask:0xf bank_mask:0xf bound_ctrl:1
	ds_read_b64 v[236:237], v182 offset:35360
	v_pk_fma_f32 v[142:143], v[154:155], v[194:195], v[142:143] op_sel_hi:[0,1,1]
	v_pk_fma_f32 v[144:145], v[154:155], v[202:203], v[144:145] op_sel_hi:[0,1,1]
	ds_read_b128 v[134:137], v183 offset:35328
	ds_read_b128 v[222:225], v183 offset:35344
	ds_read_b64 v[238:239], v183 offset:35360
	s_waitcnt lgkmcnt(6)
; __device__ __forceinline__ void wkv_phase(const WkvT& W, unsigned char* lds) {
;     ...
;                 const float* pp = sP + bo + jj * 12;
;                 const float* pv = sV + bi * 512 + il;
;                 f32x4 nA = *(const f32x4*)pp, nB = *(const f32x4*)(pp + 4); f32x2 nr = *(const f32x2*)(pp + 8); float nv = pv[0];
;                 float yk0 = 0.f, yk1 = 0.f, ep = 0.f;
;                 const bool oddrow = (lane & 16) != 0;
; #pragma unroll
;                 for (int t = 0; t < 32; ++t) {
;                     const f32x2 a2 = {nA[0], nA[1]}, w2 = {nA[2], nA[3]}, b2 = {nB[0], nB[1]}, k2 = {nB[2], nB[3]}, r2 = nr; const float v = nv;
;                     if (t + 1 < 32) { nA = *(const f32x4*)(pp + (t + 1) * 384); nB = *(const f32x4*)(pp + (t + 1) * 384 + 4); nr = *(const f32x2*)(pp + (t + 1) * 384 + 8); nv = pv[(t + 1) * 16]; }
;                     float S0 = S.x, S1 = S.y;
;                     float d = S0 * a2.x; d = __builtin_fmaf(S1, a2.y, d);
;                     float t0 = S0 * w2.x; t0 = __builtin_fmaf(v, k2.x, t0); asm volatile("" : "+v"(t0));
;                     float t1 = S1 * w2.y; t1 = __builtin_fmaf(v, k2.y, t1); asm volatile("" : "+v"(t1));
;                     float yprev; const float sa = wkv_reduce(d, ep, yprev);
;                     S0 = __builtin_fmaf(sa, b2.x, t0); asm volatile("" : "+v"(S0));
;                     S1 = __builtin_fmaf(sa, b2.y, t1); asm volatile("" : "+v"(S1));
;                     ep = S0 * r2.x; ep = __builtin_fmaf(S1, r2.y, ep);
;                     S.x = S0; S.y = S1;
	v_pk_mul_f32 v[150:151], v[142:143], v[206:207]
	v_pk_fma_f32 v[150:151], v[144:145], v[214:215], v[150:151]
	v_pk_mul_f32 v[152:153], v[142:143], v[228:229]
	v_add_f32_e32 v154, v150, v151
	v_pk_fma_f32 v[152:153], v[144:145], v[230:231], v[152:153]
	v_pk_mul_f32 v[146:147], v[142:143], v[208:209]
	v_add_f32_dpp v154, v154, v154 quad_perm:[1,0,3,2] row_mask:0xf bank_mask:0xf bound_ctrl:1
	v_pk_mul_f32 v[148:149], v[144:145], v[216:217]
	v_add_f32_e32 v161, v152, v153
	v_add_f32_dpp v154, v154, v154 quad_perm:[2,3,0,1] row_mask:0xf bank_mask:0xf bound_ctrl:1
	v_pk_fma_f32 v[146:147], v[242:243], v[212:213], v[146:147] op_sel:[0,0,0] op_sel_hi:[0,1,1]
	v_pk_fma_f32 v[148:149], v[242:243], v[220:221], v[148:149] op_sel:[0,0,0] op_sel_hi:[0,1,1]
	v_add_f32_dpp v154, v154, v154 row_half_mirror row_mask:0xf bank_mask:0xf bound_ctrl:1
	ds_read_b128 v[190:193], v182 offset:36864
	ds_read_b128 v[194:197], v182 offset:36880
	v_add_f32_dpp v154, v154, v154 row_mirror row_mask:0xf bank_mask:0xf bound_ctrl:1
	ds_read_b64 v[228:229], v182 offset:36896
	ds_read_b128 v[198:201], v183 offset:36864
	v_pk_fma_f32 v[146:147], v[154:155], v[210:211], v[146:147] op_sel_hi:[0,1,1]
	v_pk_fma_f32 v[148:149], v[154:155], v[218:219], v[148:149] op_sel_hi:[0,1,1]
	ds_read_b128 v[202:205], v183 offset:36880
	ds_read_b64 v[230:231], v183 offset:36896
	ds_read2_b32 v[240:241], v189 offset0:128 offset1:144
	s_waitcnt lgkmcnt(7)
	v_pk_mul_f32 v[150:151], v[146:147], v[126:127]
	v_pk_fma_f32 v[150:151], v[148:149], v[134:135], v[150:151]
	v_pk_mul_f32 v[152:153], v[146:147], v[232:233]
	v_add_f32_e32 v154, v150, v151
	v_pk_fma_f32 v[152:153], v[148:149], v[234:235], v[152:153]
	v_pk_mul_f32 v[142:143], v[146:147], v[128:129]
	v_add_f32_dpp v154, v154, v154 quad_perm:[1,0,3,2] row_mask:0xf bank_mask:0xf bound_ctrl:1
	v_pk_mul_f32 v[144:145], v[148:149], v[136:137]
	v_add_f32_e32 v162, v152, v153
	v_add_f32_dpp v154, v154, v154 quad_perm:[2,3,0,1] row_mask:0xf bank_mask:0xf bound_ctrl:1
	v_pk_fma_f32 v[142:143], v[242:243], v[132:133], v[142:143] op_sel:[1,0,0] op_sel_hi:[1,1,1]
	v_pk_fma_f32 v[144:145], v[242:243], v[224:225], v[144:145] op_sel:[1,0,0] op_sel_hi:[1,1,1]
	v_add_f32_dpp v154, v154, v154 row_half_mirror row_mask:0xf bank_mask:0xf bound_ctrl:1
	ds_read_b128 v[206:209], v182 offset:38400
	ds_read_b128 v[210:213], v182 offset:38416
	v_add_f32_dpp v154, v154, v154 row_mirror row_mask:0xf bank_mask:0xf bound_ctrl:1
	ds_read_b64 v[232:233], v182 offset:38432
	v_pk_fma_f32 v[142:143], v[154:155], v[130:131], v[142:143] op_sel_hi:[0,1,1]
	v_pk_fma_f32 v[144:145], v[154:155], v[222:223], v[144:145] op_sel_hi:[0,1,1]
	ds_read_b128 v[214:217], v183 offset:38400
	ds_read_b128 v[218:221], v183 offset:38416
	ds_read_b64 v[234:235], v183 offset:38432
	s_waitcnt lgkmcnt(6)
	v_pk_mul_f32 v[150:151], v[142:143], v[190:191]
	v_pk_fma_f32 v[150:151], v[144:145], v[198:199], v[150:151]
	v_pk_mul_f32 v[152:153], v[142:143], v[236:237]
	v_add_f32_e32 v154, v150, v151
	v_pk_fma_f32 v[152:153], v[144:145], v[238:239], v[152:153]
	v_pk_mul_f32 v[146:147], v[142:143], v[192:193]
	v_add_f32_dpp v154, v154, v154 quad_perm:[1,0,3,2] row_mask:0xf bank_mask:0xf bound_ctrl:1
	v_pk_mul_f32 v[148:149], v[144:145], v[200:201]
	v_add_f32_e32 v163, v152, v153
	v_add_f32_dpp v154, v154, v154 quad_perm:[2,3,0,1] row_mask:0xf bank_mask:0xf bound_ctrl:1
	v_pk_fma_f32 v[146:147], v[240:241], v[196:197], v[146:147] op_sel:[0,0,0] op_sel_hi:[0,1,1]
	v_pk_fma_f32 v[148:149], v[240:241], v[204:205], v[148:149] op_sel:[0,0,0] op_sel_hi:[0,1,1]
	v_add_f32_dpp v154, v154, v154 row_half_mirror row_mask:0xf bank_mask:0xf bound_ctrl:1
	ds_read_b128 v[126:129], v182 offset:39936
	ds_read_b128 v[130:133], v182 offset:39952
	v_add_f32_dpp v154, v154, v154 row_mirror row_mask:0xf bank_mask:0xf bound_ctrl:1
	ds_read_b64 v[236:237], v182 offset:39968
	ds_read_b128 v[134:137], v183 offset:39936
	v_pk_fma_f32 v[146:147], v[154:155], v[194:195], v[146:147] op_sel_hi:[0,1,1]
	v_pk_fma_f32 v[148:149], v[154:155], v[202:203], v[148:149] op_sel_hi:[0,1,1]
	ds_read_b128 v[222:225], v183 offset:39952
	ds_read_b64 v[238:239], v183 offset:39968
	ds_read2_b32 v[242:243], v189 offset0:160 offset1:176
	s_waitcnt lgkmcnt(7)
	v_pk_mul_f32 v[150:151], v[146:147], v[206:207]
	v_pk_fma_f32 v[150:151], v[148:149], v[214:215], v[150:151]
	v_pk_mul_f32 v[152:153], v[146:147], v[228:229]
	v_add_f32_e32 v154, v150, v151
	v_pk_fma_f32 v[152:153], v[148:149], v[230:231], v[152:153]
	v_pk_mul_f32 v[142:143], v[146:147], v[208:209]
	v_add_f32_dpp v154, v154, v154 quad_perm:[1,0,3,2] row_mask:0xf bank_mask:0xf bound_ctrl:1
	v_pk_mul_f32 v[144:145], v[148:149], v[216:217]
	v_add_f32_e32 v164, v152, v153
	v_add_f32_dpp v154, v154, v154 quad_perm:[2,3,0,1] row_mask:0xf bank_mask:0xf bound_ctrl:1
	v_pk_fma_f32 v[142:143], v[240:241], v[212:213], v[142:143] op_sel:[1,0,0] op_sel_hi:[1,1,1]
	v_pk_fma_f32 v[144:145], v[240:241], v[220:221], v[144:145] op_sel:[1,0,0] op_sel_hi:[1,1,1]
	v_add_f32_dpp v154, v154, v154 row_half_mirror row_mask:0xf bank_mask:0xf bound_ctrl:1
	ds_read_b128 v[190:193], v182 offset:41472
	ds_read_b128 v[194:197], v182 offset:41488
	v_add_f32_dpp v154, v154, v154 row_mirror row_mask:0xf bank_mask:0xf bound_ctrl:1
	ds_read_b64 v[228:229], v182 offset:41504
	v_pk_fma_f32 v[142:143], v[154:155], v[210:211], v[142:143] op_sel_hi:[0,1,1]
	v_pk_fma_f32 v[144:145], v[154:155], v[218:219], v[144:145] op_sel_hi:[0,1,1]
	ds_read_b128 v[198:201], v183 offset:41472
	ds_read_b128 v[202:205], v183 offset:41488
	ds_read_b64 v[230:231], v183 offset:41504
	s_waitcnt lgkmcnt(6)
; __device__ __forceinline__ void wkv_phase(const WkvT& W, unsigned char* lds) {
;     ...
;                 const float* pp = sP + bo + jj * 12;
;                 const float* pv = sV + bi * 512 + il;
;                 f32x4 nA = *(const f32x4*)pp, nB = *(const f32x4*)(pp + 4); f32x2 nr = *(const f32x2*)(pp + 8); float nv = pv[0];
;                 float yk0 = 0.f, yk1 = 0.f, ep = 0.f;
;                 const bool oddrow = (lane & 16) != 0;
; #pragma unroll
;                 for (int t = 0; t < 32; ++t) {
;                     const f32x2 a2 = {nA[0], nA[1]}, w2 = {nA[2], nA[3]}, b2 = {nB[0], nB[1]}, k2 = {nB[2], nB[3]}, r2 = nr; const float v = nv;
;                     if (t + 1 < 32) { nA = *(const f32x4*)(pp + (t + 1) * 384); nB = *(const f32x4*)(pp + (t + 1) * 384 + 4); nr = *(const f32x2*)(pp + (t + 1) * 384 + 8); nv = pv[(t + 1) * 16]; }
;                     float S0 = S.x, S1 = S.y;
;                     float d = S0 * a2.x; d = __builtin_fmaf(S1, a2.y, d);
;                     float t0 = S0 * w2.x; t0 = __builtin_fmaf(v, k2.x, t0); asm volatile("" : "+v"(t0));
;                     float t1 = S1 * w2.y; t1 = __builtin_fmaf(v, k2.y, t1); asm volatile("" : "+v"(t1));
;                     float yprev; const float sa = wkv_reduce(d, ep, yprev);
;                     S0 = __builtin_fmaf(sa, b2.x, t0); asm volatile("" : "+v"(S0));
;                     S1 = __builtin_fmaf(sa, b2.y, t1); asm volatile("" : "+v"(S1));
;                     ep = S0 * r2.x; ep = __builtin_fmaf(S1, r2.y, ep);
;                     S.x = S0; S.y = S1;
	v_pk_mul_f32 v[150:151], v[142:143], v[126:127]
	v_pk_fma_f32 v[150:151], v[144:145], v[134:135], v[150:151]
	v_pk_mul_f32 v[152:153], v[142:143], v[232:233]
	v_add_f32_e32 v154, v150, v151
	v_pk_fma_f32 v[152:153], v[144:145], v[234:235], v[152:153]
	v_pk_mul_f32 v[146:147], v[142:143], v[128:129]
	v_add_f32_dpp v154, v154, v154 quad_perm:[1,0,3,2] row_mask:0xf bank_mask:0xf bound_ctrl:1
	v_pk_mul_f32 v[148:149], v[144:145], v[136:137]
	v_add_f32_e32 v165, v152, v153
	v_add_f32_dpp v154, v154, v154 quad_perm:[2,3,0,1] row_mask:0xf bank_mask:0xf bound_ctrl:1
	v_pk_fma_f32 v[146:147], v[242:243], v[132:133], v[146:147] op_sel:[0,0,0] op_sel_hi:[0,1,1]
	v_pk_fma_f32 v[148:149], v[242:243], v[224:225], v[148:149] op_sel:[0,0,0] op_sel_hi:[0,1,1]
	v_add_f32_dpp v154, v154, v154 row_half_mirror row_mask:0xf bank_mask:0xf bound_ctrl:1
	ds_read_b128 v[206:209], v182 offset:43008
	ds_read_b128 v[210:213], v182 offset:43024
	v_add_f32_dpp v154, v154, v154 row_mirror row_mask:0xf bank_mask:0xf bound_ctrl:1
	ds_read_b64 v[232:233], v182 offset:43040
	ds_read_b128 v[214:217], v183 offset:43008
	v_pk_fma_f32 v[146:147], v[154:155], v[130:131], v[146:147] op_sel_hi:[0,1,1]
	v_pk_fma_f32 v[148:149], v[154:155], v[222:223], v[148:149] op_sel_hi:[0,1,1]
	ds_read_b128 v[218:221], v183 offset:43024
	ds_read_b64 v[234:235], v183 offset:43040
	ds_read2_b32 v[240:241], v189 offset0:192 offset1:208
	s_waitcnt lgkmcnt(7)
	v_pk_mul_f32 v[150:151], v[146:147], v[190:191]
	v_pk_fma_f32 v[150:151], v[148:149], v[198:199], v[150:151]
	v_pk_mul_f32 v[152:153], v[146:147], v[236:237]
	v_add_f32_e32 v154, v150, v151
	v_pk_fma_f32 v[152:153], v[148:149], v[238:239], v[152:153]
	v_pk_mul_f32 v[142:143], v[146:147], v[192:193]
	v_add_f32_dpp v154, v154, v154 quad_perm:[1,0,3,2] row_mask:0xf bank_mask:0xf bound_ctrl:1
	v_pk_mul_f32 v[144:145], v[148:149], v[200:201]
	v_add_f32_e32 v166, v152, v153
	v_add_f32_dpp v154, v154, v154 quad_perm:[2,3,0,1] row_mask:0xf bank_mask:0xf bound_ctrl:1
	v_pk_fma_f32 v[142:143], v[242:243], v[196:197], v[142:143] op_sel:[1,0,0] op_sel_hi:[1,1,1]
	v_pk_fma_f32 v[144:145], v[242:243], v[204:205], v[144:145] op_sel:[1,0,0] op_sel_hi:[1,1,1]
	v_add_f32_dpp v154, v154, v154 row_half_mirror row_mask:0xf bank_mask:0xf bound_ctrl:1
	ds_read_b128 v[126:129], v182 offset:44544
	ds_read_b128 v[130:133], v182 offset:44560
	v_add_f32_dpp v154, v154, v154 row_mirror row_mask:0xf bank_mask:0xf bound_ctrl:1
	ds_read_b64 v[236:237], v182 offset:44576
	v_pk_fma_f32 v[142:143], v[154:155], v[194:195], v[142:143] op_sel_hi:[0,1,1]
	v_pk_fma_f32 v[144:145], v[154:155], v[202:203], v[144:145] op_sel_hi:[0,1,1]
	ds_read_b128 v[134:137], v183 offset:44544
	ds_read_b128 v[222:225], v183 offset:44560
	ds_read_b64 v[238:239], v183 offset:44576
	s_waitcnt lgkmcnt(6)
	v_pk_mul_f32 v[150:151], v[142:143], v[206:207]
	v_pk_fma_f32 v[150:151], v[144:145], v[214:215], v[150:151]
	v_pk_mul_f32 v[152:153], v[142:143], v[228:229]
	v_add_f32_e32 v154, v150, v151
	v_pk_fma_f32 v[152:153], v[144:145], v[230:231], v[152:153]
	v_pk_mul_f32 v[146:147], v[142:143], v[208:209]
	v_add_f32_dpp v154, v154, v154 quad_perm:[1,0,3,2] row_mask:0xf bank_mask:0xf bound_ctrl:1
	v_pk_mul_f32 v[148:149], v[144:145], v[216:217]
	v_add_f32_e32 v167, v152, v153
	v_add_f32_dpp v154, v154, v154 quad_perm:[2,3,0,1] row_mask:0xf bank_mask:0xf bound_ctrl:1
	v_pk_fma_f32 v[146:147], v[240:241], v[212:213], v[146:147] op_sel:[0,0,0] op_sel_hi:[0,1,1]
	v_pk_fma_f32 v[148:149], v[240:241], v[220:221], v[148:149] op_sel:[0,0,0] op_sel_hi:[0,1,1]
	v_add_f32_dpp v154, v154, v154 row_half_mirror row_mask:0xf bank_mask:0xf bound_ctrl:1
	ds_read_b128 v[190:193], v182 offset:46080
	ds_read_b128 v[194:197], v182 offset:46096
	v_add_f32_dpp v154, v154, v154 row_mirror row_mask:0xf bank_mask:0xf bound_ctrl:1
	ds_read_b64 v[228:229], v182 offset:46112
	ds_read_b128 v[198:201], v183 offset:46080
	v_pk_fma_f32 v[146:147], v[154:155], v[210:211], v[146:147] op_sel_hi:[0,1,1]
	v_pk_fma_f32 v[148:149], v[154:155], v[218:219], v[148:149] op_sel_hi:[0,1,1]
	ds_read_b128 v[202:205], v183 offset:46096
	ds_read_b64 v[230:231], v183 offset:46112
	ds_read2_b32 v[242:243], v189 offset0:224 offset1:240
	s_waitcnt lgkmcnt(7)
	v_pk_mul_f32 v[150:151], v[146:147], v[126:127]
	v_pk_fma_f32 v[150:151], v[148:149], v[134:135], v[150:151]
	v_pk_mul_f32 v[152:153], v[146:147], v[232:233]
	v_add_f32_e32 v154, v150, v151
	v_pk_fma_f32 v[152:153], v[148:149], v[234:235], v[152:153]
	v_pk_mul_f32 v[142:143], v[146:147], v[128:129]
	v_add_f32_dpp v154, v154, v154 quad_perm:[1,0,3,2] row_mask:0xf bank_mask:0xf bound_ctrl:1
	v_pk_mul_f32 v[144:145], v[148:149], v[136:137]
	v_add_f32_e32 v168, v152, v153
	v_add_f32_dpp v154, v154, v154 quad_perm:[2,3,0,1] row_mask:0xf bank_mask:0xf bound_ctrl:1
	v_pk_fma_f32 v[142:143], v[240:241], v[132:133], v[142:143] op_sel:[1,0,0] op_sel_hi:[1,1,1]
	v_pk_fma_f32 v[144:145], v[240:241], v[224:225], v[144:145] op_sel:[1,0,0] op_sel_hi:[1,1,1]
	v_add_f32_dpp v154, v154, v154 row_half_mirror row_mask:0xf bank_mask:0xf bound_ctrl:1
	ds_read_b128 v[206:209], v182 offset:47616
	ds_read_b128 v[210:213], v182 offset:47632
	v_add_f32_dpp v154, v154, v154 row_mirror row_mask:0xf bank_mask:0xf bound_ctrl:1
	ds_read_b64 v[232:233], v182 offset:47648
	v_pk_fma_f32 v[142:143], v[154:155], v[130:131], v[142:143] op_sel_hi:[0,1,1]
	v_pk_fma_f32 v[144:145], v[154:155], v[222:223], v[144:145] op_sel_hi:[0,1,1]
	ds_read_b128 v[214:217], v183 offset:47616
	ds_read_b128 v[218:221], v183 offset:47632
	ds_read_b64 v[234:235], v183 offset:47648
	s_waitcnt lgkmcnt(6)
; __device__ __forceinline__ void wkv_phase(const WkvT& W, unsigned char* lds) {
;     ...
;                 const float* pp = sP + bo + jj * 12;
;                 const float* pv = sV + bi * 512 + il;
;                 f32x4 nA = *(const f32x4*)pp, nB = *(const f32x4*)(pp + 4); f32x2 nr = *(const f32x2*)(pp + 8); float nv = pv[0];
;                 float yk0 = 0.f, yk1 = 0.f, ep = 0.f;
;                 const bool oddrow = (lane & 16) != 0;
; #pragma unroll
;                 for (int t = 0; t < 32; ++t) {
;                     const f32x2 a2 = {nA[0], nA[1]}, w2 = {nA[2], nA[3]}, b2 = {nB[0], nB[1]}, k2 = {nB[2], nB[3]}, r2 = nr; const float v = nv;
;                     if (t + 1 < 32) { nA = *(const f32x4*)(pp + (t + 1) * 384); nB = *(const f32x4*)(pp + (t + 1) * 384 + 4); nr = *(const f32x2*)(pp + (t + 1) * 384 + 8); nv = pv[(t + 1) * 16]; }
;                     float S0 = S.x, S1 = S.y;
;                     float d = S0 * a2.x; d = __builtin_fmaf(S1, a2.y, d);
;                     float t0 = S0 * w2.x; t0 = __builtin_fmaf(v, k2.x, t0); asm volatile("" : "+v"(t0));
;                     float t1 = S1 * w2.y; t1 = __builtin_fmaf(v, k2.y, t1); asm volatile("" : "+v"(t1));
;                     float yprev; const float sa = wkv_reduce(d, ep, yprev);
;                     S0 = __builtin_fmaf(sa, b2.x, t0); asm volatile("" : "+v"(S0));
;                     S1 = __builtin_fmaf(sa, b2.y, t1); asm volatile("" : "+v"(S1));
;                     ep = S0 * r2.x; ep = __builtin_fmaf(S1, r2.y, ep);
;                     S.x = S0; S.y = S1;
;                     if (t >= 1) { const bool hit = oddrow && ((lane & 15) == ((t - 1) & 15)); if (t <= 16) yk0 = hit ? yprev : yk0; else yk1 = hit ? yprev : yk1; }
;                 }
;                 { float ylast; (void)wkv_reduce(0.f, ep, ylast); yk1 = (oddrow && (lane & 15) == 15) ? ylast : yk1; }
;                 if (oddrow) { sY[bi * 512 + (lane & 15) * 16 + il] = yk0; sY[bi * 512 + (16 + (lane & 15)) * 16 + il] = yk1; }
	v_pk_mul_f32 v[150:151], v[142:143], v[190:191]
	v_pk_fma_f32 v[150:151], v[144:145], v[198:199], v[150:151]
	v_pk_mul_f32 v[152:153], v[142:143], v[236:237]
	v_add_f32_e32 v154, v150, v151
	v_pk_fma_f32 v[152:153], v[144:145], v[238:239], v[152:153]
	v_pk_mul_f32 v[146:147], v[142:143], v[192:193]
	v_add_f32_dpp v154, v154, v154 quad_perm:[1,0,3,2] row_mask:0xf bank_mask:0xf bound_ctrl:1
	v_pk_mul_f32 v[148:149], v[144:145], v[200:201]
	v_add_f32_e32 v169, v152, v153
	v_add_f32_dpp v154, v154, v154 quad_perm:[2,3,0,1] row_mask:0xf bank_mask:0xf bound_ctrl:1
	v_pk_fma_f32 v[146:147], v[242:243], v[196:197], v[146:147] op_sel:[0,0,0] op_sel_hi:[0,1,1]
	v_pk_fma_f32 v[148:149], v[242:243], v[204:205], v[148:149] op_sel:[0,0,0] op_sel_hi:[0,1,1]
	v_add_f32_dpp v154, v154, v154 row_half_mirror row_mask:0xf bank_mask:0xf bound_ctrl:1
	s_nop 1
	v_add_f32_dpp v154, v154, v154 row_mirror row_mask:0xf bank_mask:0xf bound_ctrl:1
	v_pk_fma_f32 v[146:147], v[154:155], v[194:195], v[146:147] op_sel_hi:[0,1,1]
	v_pk_fma_f32 v[148:149], v[154:155], v[202:203], v[148:149] op_sel_hi:[0,1,1]
	s_waitcnt lgkmcnt(0)
	v_pk_mul_f32 v[150:151], v[146:147], v[206:207]
	v_pk_fma_f32 v[150:151], v[148:149], v[214:215], v[150:151]
	v_pk_mul_f32 v[152:153], v[146:147], v[228:229]
	v_add_f32_e32 v154, v150, v151
	v_pk_fma_f32 v[152:153], v[148:149], v[230:231], v[152:153]
	v_pk_mul_f32 v[142:143], v[146:147], v[208:209]
	v_add_f32_dpp v154, v154, v154 quad_perm:[1,0,3,2] row_mask:0xf bank_mask:0xf bound_ctrl:1
	v_pk_mul_f32 v[144:145], v[148:149], v[216:217]
	v_add_f32_e32 v170, v152, v153
	v_add_f32_dpp v154, v154, v154 quad_perm:[2,3,0,1] row_mask:0xf bank_mask:0xf bound_ctrl:1
	v_pk_fma_f32 v[142:143], v[242:243], v[212:213], v[142:143] op_sel:[1,0,0] op_sel_hi:[1,1,1]
	v_pk_fma_f32 v[144:145], v[242:243], v[220:221], v[144:145] op_sel:[1,0,0] op_sel_hi:[1,1,1]
	v_add_f32_dpp v154, v154, v154 row_half_mirror row_mask:0xf bank_mask:0xf bound_ctrl:1
	s_nop 1
	v_add_f32_dpp v154, v154, v154 row_mirror row_mask:0xf bank_mask:0xf bound_ctrl:1
	v_pk_fma_f32 v[142:143], v[154:155], v[210:211], v[142:143] op_sel_hi:[0,1,1]
	v_pk_fma_f32 v[144:145], v[154:155], v[218:219], v[144:145] op_sel_hi:[0,1,1]
	v_pk_mul_f32 v[152:153], v[142:143], v[232:233]
	v_pk_fma_f32 v[152:153], v[144:145], v[234:235], v[152:153]
	s_nop 0
	v_add_f32_e32 v171, v152, v153
	v_add_f32_dpp v172, v156, v156 row_ror:8 row_mask:0xf bank_mask:0x3
	v_add_f32_dpp v173, v157, v157 row_ror:8 row_mask:0xf bank_mask:0x3
	v_add_f32_dpp v174, v158, v158 row_ror:8 row_mask:0xf bank_mask:0x3
	v_add_f32_dpp v175, v159, v159 row_ror:8 row_mask:0xf bank_mask:0x3
	v_add_f32_dpp v176, v160, v160 row_ror:8 row_mask:0xf bank_mask:0x3
	v_add_f32_dpp v177, v161, v161 row_ror:8 row_mask:0xf bank_mask:0x3
	v_add_f32_dpp v178, v162, v162 row_ror:8 row_mask:0xf bank_mask:0x3
	v_add_f32_dpp v179, v163, v163 row_ror:8 row_mask:0xf bank_mask:0x3
	v_add_f32_dpp v172, v164, v164 row_ror:8 row_mask:0xf bank_mask:0xc
	v_add_f32_dpp v173, v165, v165 row_ror:8 row_mask:0xf bank_mask:0xc
	v_add_f32_dpp v174, v166, v166 row_ror:8 row_mask:0xf bank_mask:0xc
	v_add_f32_dpp v175, v167, v167 row_ror:8 row_mask:0xf bank_mask:0xc
	v_add_f32_dpp v176, v168, v168 row_ror:8 row_mask:0xf bank_mask:0xc
	v_add_f32_dpp v177, v169, v169 row_ror:8 row_mask:0xf bank_mask:0xc
	v_add_f32_dpp v178, v170, v170 row_ror:8 row_mask:0xf bank_mask:0xc
	v_add_f32_dpp v179, v171, v171 row_ror:8 row_mask:0xf bank_mask:0xc
	v_add_f32_dpp v156, v172, v172 row_half_mirror row_mask:0xf bank_mask:0x5
	v_add_f32_dpp v157, v173, v173 row_half_mirror row_mask:0xf bank_mask:0x5
	v_add_f32_dpp v158, v174, v174 row_half_mirror row_mask:0xf bank_mask:0x5
	v_add_f32_dpp v159, v175, v175 row_half_mirror row_mask:0xf bank_mask:0x5
	v_add_f32_dpp v156, v176, v176 row_half_mirror row_mask:0xf bank_mask:0xa
	v_add_f32_dpp v157, v177, v177 row_half_mirror row_mask:0xf bank_mask:0xa
	v_add_f32_dpp v158, v178, v178 row_half_mirror row_mask:0xf bank_mask:0xa
	v_add_f32_dpp v159, v179, v179 row_half_mirror row_mask:0xf bank_mask:0xa
	v_cndmask_b32_e64 v178, v156, v158, s[14:15]
	v_cndmask_b32_e64 v176, v158, v156, s[14:15]
	v_cndmask_b32_e64 v179, v157, v159, s[14:15]
	v_cndmask_b32_e64 v177, v159, v157, s[14:15]
	s_nop 1
	v_add_f32_dpp v172, v176, v178 quad_perm:[2,3,0,1] row_mask:0xf bank_mask:0xf
	v_add_f32_dpp v173, v177, v179 quad_perm:[2,3,0,1] row_mask:0xf bank_mask:0xf
	v_cndmask_b32_e64 v176, v173, v172, s[16:17]
	v_cndmask_b32_e64 v178, v172, v173, s[16:17]
	s_nop 1
	v_add_f32_dpp v181, v176, v178 quad_perm:[1,0,3,2] row_mask:0xf bank_mask:0xf
	ds_write2st64_b32 v187, v180, v181 offset0:0 offset1:4

; __device__ __forceinline__ void wkv_phase(const WkvT& W, unsigned char* lds) {
;     ...
;             if (c + 1 < 256) wkv_issue(W, raw, rowbase, cbase, q, c + 1, tid);
;             {
;                 const float* pp = sP + bo + jj * 12;
;                 const float* pv = sV + bi * 512 + il;
;                 f32x4 nA = *(const f32x4*)pp, nB = *(const f32x4*)(pp + 4); f32x2 nr = *(const f32x2*)(pp + 8); float nv = pv[0];
;                 float yk0 = 0.f, yk1 = 0.f, ep = 0.f;
;                 const bool oddrow = (lane & 16) != 0;
; #pragma unroll
;                 for (int t = 0; t < 32; ++t) {
;                     const f32x2 a2 = {nA[0], nA[1]}, w2 = {nA[2], nA[3]}, b2 = {nB[0], nB[1]}, k2 = {nB[2], nB[3]}, r2 = nr; const float v = nv;
;                     if (t + 1 < 32) { nA = *(const f32x4*)(pp + (t + 1) * 384); nB = *(const f32x4*)(pp + (t + 1) * 384 + 4); nr = *(const f32x2*)(pp + (t + 1) * 384 + 8); nv = pv[(t + 1) * 16]; }
;                     float S0 = S.x, S1 = S.y;
;                     float d = S0 * a2.x; d = __builtin_fmaf(S1, a2.y, d);
;                     float t0 = S0 * w2.x; t0 = __builtin_fmaf(v, k2.x, t0); asm volatile("" : "+v"(t0));
;                     float t1 = S1 * w2.y; t1 = __builtin_fmaf(v, k2.y, t1); asm volatile("" : "+v"(t1));
;                     float yprev; const float sa = wkv_reduce(d, ep, yprev);
;                     S0 = __builtin_fmaf(sa, b2.x, t0); asm volatile("" : "+v"(S0));
;                     S1 = __builtin_fmaf(sa, b2.y, t1); asm volatile("" : "+v"(S1));
;                     ep = S0 * r2.x; ep = __builtin_fmaf(S1, r2.y, ep);
;                     S.x = S0; S.y = S1;
.LBB0_1636:
	s_bitcmp1_b32 s99, 8
	s_cbranch_scc1 .Lwkv4_b2_skip
	ds_read_b128 v[190:193], v182 offset:49152
	ds_read_b128 v[194:197], v182 offset:49168
	ds_read_b64 v[228:229], v182 offset:49184
	ds_read_b128 v[198:201], v183 offset:49152
	ds_read_b128 v[202:205], v183 offset:49168
	ds_read_b64 v[230:231], v183 offset:49184
	ds_read2_b32 v[240:241], v226 offset0:0 offset1:16
	ds_read_b128 v[206:209], v182 offset:50688
	ds_read_b128 v[210:213], v182 offset:50704
	ds_read_b64 v[232:233], v182 offset:50720
	ds_read_b128 v[214:217], v183 offset:50688
	ds_read_b128 v[218:221], v183 offset:50704
	ds_read_b64 v[234:235], v183 offset:50720
	s_waitcnt lgkmcnt(6)
	v_pk_mul_f32 v[150:151], v[142:143], v[190:191]
	v_pk_fma_f32 v[150:151], v[144:145], v[198:199], v[150:151]
	v_pk_mul_f32 v[146:147], v[142:143], v[192:193]
	v_add_f32_e32 v154, v150, v151
	v_pk_mul_f32 v[148:149], v[144:145], v[200:201]
	v_pk_fma_f32 v[146:147], v[240:241], v[196:197], v[146:147] op_sel:[0,0,0] op_sel_hi:[0,1,1]
	v_add_f32_dpp v154, v154, v154 quad_perm:[1,0,3,2] row_mask:0xf bank_mask:0xf bound_ctrl:1
	v_pk_fma_f32 v[148:149], v[240:241], v[204:205], v[148:149] op_sel:[0,0,0] op_sel_hi:[0,1,1]
	s_nop 0
	v_add_f32_dpp v154, v154, v154 quad_perm:[2,3,0,1] row_mask:0xf bank_mask:0xf bound_ctrl:1
	ds_read_b128 v[126:129], v182 offset:52224
	ds_read_b128 v[130:133], v182 offset:52240
	v_add_f32_dpp v154, v154, v154 row_half_mirror row_mask:0xf bank_mask:0xf bound_ctrl:1
	ds_read_b64 v[236:237], v182 offset:52256
	ds_read_b128 v[134:137], v183 offset:52224
	v_add_f32_dpp v154, v154, v154 row_mirror row_mask:0xf bank_mask:0xf bound_ctrl:1
	v_pk_fma_f32 v[146:147], v[154:155], v[194:195], v[146:147] op_sel_hi:[0,1,1]
	v_pk_fma_f32 v[148:149], v[154:155], v[202:203], v[148:149] op_sel_hi:[0,1,1]
	ds_read_b128 v[222:225], v183 offset:52240
	ds_read_b64 v[238:239], v183 offset:52256
	ds_read2_b32 v[242:243], v226 offset0:32 offset1:48
	s_waitcnt lgkmcnt(7)
	v_pk_mul_f32 v[150:151], v[146:147], v[206:207]
	v_pk_fma_f32 v[150:151], v[148:149], v[214:215], v[150:151]
	v_pk_mul_f32 v[152:153], v[146:147], v[228:229]
	v_add_f32_e32 v154, v150, v151
	v_pk_fma_f32 v[152:153], v[148:149], v[230:231], v[152:153]
	v_pk_mul_f32 v[142:143], v[146:147], v[208:209]
	v_add_f32_dpp v154, v154, v154 quad_perm:[1,0,3,2] row_mask:0xf bank_mask:0xf bound_ctrl:1
	v_pk_mul_f32 v[144:145], v[148:149], v[216:217]
	v_add_f32_e32 v156, v152, v153
	v_add_f32_dpp v154, v154, v154 quad_perm:[2,3,0,1] row_mask:0xf bank_mask:0xf bound_ctrl:1
	v_pk_fma_f32 v[142:143], v[240:241], v[212:213], v[142:143] op_sel:[1,0,0] op_sel_hi:[1,1,1]
	v_pk_fma_f32 v[144:145], v[240:241], v[220:221], v[144:145] op_sel:[1,0,0] op_sel_hi:[1,1,1]
	v_add_f32_dpp v154, v154, v154 row_half_mirror row_mask:0xf bank_mask:0xf bound_ctrl:1
	ds_read_b128 v[190:193], v182 offset:53760
	ds_read_b128 v[194:197], v182 offset:53776
	v_add_f32_dpp v154, v154, v154 row_mirror row_mask:0xf bank_mask:0xf bound_ctrl:1
	ds_read_b64 v[228:229], v182 offset:53792
	v_pk_fma_f32 v[142:143], v[154:155], v[210:211], v[142:143] op_sel_hi:[0,1,1]
	v_pk_fma_f32 v[144:145], v[154:155], v[218:219], v[144:145] op_sel_hi:[0,1,1]
	ds_read_b128 v[198:201], v183 offset:53760
	ds_read_b128 v[202:205], v183 offset:53776
	ds_read_b64 v[230:231], v183 offset:53792
	s_waitcnt lgkmcnt(6)
	v_pk_mul_f32 v[150:151], v[142:143], v[126:127]
	v_pk_fma_f32 v[150:151], v[144:145], v[134:135], v[150:151]
	v_pk_mul_f32 v[152:153], v[142:143], v[232:233]
	v_add_f32_e32 v154, v150, v151
	v_pk_fma_f32 v[152:153], v[144:145], v[234:235], v[152:153]
	v_pk_mul_f32 v[146:147], v[142:143], v[128:129]
	v_add_f32_dpp v154, v154, v154 quad_perm:[1,0,3,2] row_mask:0xf bank_mask:0xf bound_ctrl:1
	v_pk_mul_f32 v[148:149], v[144:145], v[136:137]
	v_add_f32_e32 v157, v152, v153
	v_add_f32_dpp v154, v154, v154 quad_perm:[2,3,0,1] row_mask:0xf bank_mask:0xf bound_ctrl:1
	v_pk_fma_f32 v[146:147], v[242:243], v[132:133], v[146:147] op_sel:[0,0,0] op_sel_hi:[0,1,1]
	v_pk_fma_f32 v[148:149], v[242:243], v[224:225], v[148:149] op_sel:[0,0,0] op_sel_hi:[0,1,1]
	v_add_f32_dpp v154, v154, v154 row_half_mirror row_mask:0xf bank_mask:0xf bound_ctrl:1
	ds_read_b128 v[206:209], v182 offset:55296
	ds_read_b128 v[210:213], v182 offset:55312
	v_add_f32_dpp v154, v154, v154 row_mirror row_mask:0xf bank_mask:0xf bound_ctrl:1
	ds_read_b64 v[232:233], v182 offset:55328
	ds_read_b128 v[214:217], v183 offset:55296
	v_pk_fma_f32 v[146:147], v[154:155], v[130:131], v[146:147] op_sel_hi:[0,1,1]
	v_pk_fma_f32 v[148:149], v[154:155], v[222:223], v[148:149] op_sel_hi:[0,1,1]
	ds_read_b128 v[218:221], v183 offset:55312
	ds_read_b64 v[234:235], v183 offset:55328
	ds_read2_b32 v[240:241], v226 offset0:64 offset1:80
	s_waitcnt lgkmcnt(7)
	v_pk_mul_f32 v[150:151], v[146:147], v[190:191]
	v_pk_fma_f32 v[150:151], v[148:149], v[198:199], v[150:151]
	v_pk_mul_f32 v[152:153], v[146:147], v[236:237]
	v_add_f32_e32 v154, v150, v151
	v_pk_fma_f32 v[152:153], v[148:149], v[238:239], v[152:153]
	v_pk_mul_f32 v[142:143], v[146:147], v[192:193]
	v_add_f32_dpp v154, v154, v154 quad_perm:[1,0,3,2] row_mask:0xf bank_mask:0xf bound_ctrl:1
	v_pk_mul_f32 v[144:145], v[148:149], v[200:201]
	v_add_f32_e32 v158, v152, v153
	v_add_f32_dpp v154, v154, v154 quad_perm:[2,3,0,1] row_mask:0xf bank_mask:0xf bound_ctrl:1
	v_pk_fma_f32 v[142:143], v[242:243], v[196:197], v[142:143] op_sel:[1,0,0] op_sel_hi:[1,1,1]
	v_pk_fma_f32 v[144:145], v[242:243], v[204:205], v[144:145] op_sel:[1,0,0] op_sel_hi:[1,1,1]
	v_add_f32_dpp v154, v154, v154 row_half_mirror row_mask:0xf bank_mask:0xf bound_ctrl:1
	ds_read_b128 v[126:129], v182 offset:56832
	ds_read_b128 v[130:133], v182 offset:56848
	v_add_f32_dpp v154, v154, v154 row_mirror row_mask:0xf bank_mask:0xf bound_ctrl:1
	ds_read_b64 v[236:237], v182 offset:56864
	v_pk_fma_f32 v[142:143], v[154:155], v[194:195], v[142:143] op_sel_hi:[0,1,1]
	v_pk_fma_f32 v[144:145], v[154:155], v[202:203], v[144:145] op_sel_hi:[0,1,1]
	ds_read_b128 v[134:137], v183 offset:56832
	ds_read_b128 v[222:225], v183 offset:56848
	ds_read_b64 v[238:239], v183 offset:56864
	s_waitcnt lgkmcnt(6)
; __device__ __forceinline__ void wkv_phase(const WkvT& W, unsigned char* lds) {
;     ...
;                 for (int t = 0; t < 32; ++t) {
;                     const f32x2 a2 = {nA[0], nA[1]}, w2 = {nA[2], nA[3]}, b2 = {nB[0], nB[1]}, k2 = {nB[2], nB[3]}, r2 = nr; const float v = nv;
;                     if (t + 1 < 32) { nA = *(const f32x4*)(pp + (t + 1) * 384); nB = *(const f32x4*)(pp + (t + 1) * 384 + 4); nr = *(const f32x2*)(pp + (t + 1) * 384 + 8); nv = pv[(t + 1) * 16]; }
;                     float S0 = S.x, S1 = S.y;
;                     float d = S0 * a2.x; d = __builtin_fmaf(S1, a2.y, d);
;                     float t0 = S0 * w2.x; t0 = __builtin_fmaf(v, k2.x, t0); asm volatile("" : "+v"(t0));
;                     float t1 = S1 * w2.y; t1 = __builtin_fmaf(v, k2.y, t1); asm volatile("" : "+v"(t1));
;                     float yprev; const float sa = wkv_reduce(d, ep, yprev);
;                     S0 = __builtin_fmaf(sa, b2.x, t0); asm volatile("" : "+v"(S0));
;                     S1 = __builtin_fmaf(sa, b2.y, t1); asm volatile("" : "+v"(S1));
;                     ep = S0 * r2.x; ep = __builtin_fmaf(S1, r2.y, ep);
;                     S.x = S0; S.y = S1;
	v_pk_mul_f32 v[150:151], v[142:143], v[206:207]
	v_pk_fma_f32 v[150:151], v[144:145], v[214:215], v[150:151]
	v_pk_mul_f32 v[152:153], v[142:143], v[228:229]
	v_add_f32_e32 v154, v150, v151
	v_pk_fma_f32 v[152:153], v[144:145], v[230:231], v[152:153]
	v_pk_mul_f32 v[146:147], v[142:143], v[208:209]
	v_add_f32_dpp v154, v154, v154 quad_perm:[1,0,3,2] row_mask:0xf bank_mask:0xf bound_ctrl:1
	v_pk_mul_f32 v[148:149], v[144:145], v[216:217]
	v_add_f32_e32 v159, v152, v153
	v_add_f32_dpp v154, v154, v154 quad_perm:[2,3,0,1] row_mask:0xf bank_mask:0xf bound_ctrl:1
	v_pk_fma_f32 v[146:147], v[240:241], v[212:213], v[146:147] op_sel:[0,0,0] op_sel_hi:[0,1,1]
	v_pk_fma_f32 v[148:149], v[240:241], v[220:221], v[148:149] op_sel:[0,0,0] op_sel_hi:[0,1,1]
	v_add_f32_dpp v154, v154, v154 row_half_mirror row_mask:0xf bank_mask:0xf bound_ctrl:1
	ds_read_b128 v[190:193], v182 offset:58368
	ds_read_b128 v[194:197], v182 offset:58384
	v_add_f32_dpp v154, v154, v154 row_mirror row_mask:0xf bank_mask:0xf bound_ctrl:1
	ds_read_b64 v[228:229], v182 offset:58400
	ds_read_b128 v[198:201], v183 offset:58368
	v_pk_fma_f32 v[146:147], v[154:155], v[210:211], v[146:147] op_sel_hi:[0,1,1]
	v_pk_fma_f32 v[148:149], v[154:155], v[218:219], v[148:149] op_sel_hi:[0,1,1]
	ds_read_b128 v[202:205], v183 offset:58384
	ds_read_b64 v[230:231], v183 offset:58400
	ds_read2_b32 v[242:243], v226 offset0:96 offset1:112
	s_waitcnt lgkmcnt(7)
	v_pk_mul_f32 v[150:151], v[146:147], v[126:127]
	v_pk_fma_f32 v[150:151], v[148:149], v[134:135], v[150:151]
	v_pk_mul_f32 v[152:153], v[146:147], v[232:233]
	v_add_f32_e32 v154, v150, v151
	v_pk_fma_f32 v[152:153], v[148:149], v[234:235], v[152:153]
	v_pk_mul_f32 v[142:143], v[146:147], v[128:129]
	v_add_f32_dpp v154, v154, v154 quad_perm:[1,0,3,2] row_mask:0xf bank_mask:0xf bound_ctrl:1
	v_pk_mul_f32 v[144:145], v[148:149], v[136:137]
	v_add_f32_e32 v160, v152, v153
	v_add_f32_dpp v154, v154, v154 quad_perm:[2,3,0,1] row_mask:0xf bank_mask:0xf bound_ctrl:1
	v_pk_fma_f32 v[142:143], v[240:241], v[132:133], v[142:143] op_sel:[1,0,0] op_sel_hi:[1,1,1]
	v_pk_fma_f32 v[144:145], v[240:241], v[224:225], v[144:145] op_sel:[1,0,0] op_sel_hi:[1,1,1]
	v_add_f32_dpp v154, v154, v154 row_half_mirror row_mask:0xf bank_mask:0xf bound_ctrl:1
	ds_read_b128 v[206:209], v182 offset:59904
	ds_read_b128 v[210:213], v182 offset:59920
	v_add_f32_dpp v154, v154, v154 row_mirror row_mask:0xf bank_mask:0xf bound_ctrl:1
	ds_read_b64 v[232:233], v182 offset:59936
	v_pk_fma_f32 v[142:143], v[154:155], v[130:131], v[142:143] op_sel_hi:[0,1,1]
	v_pk_fma_f32 v[144:145], v[154:155], v[222:223], v[144:145] op_sel_hi:[0,1,1]
	ds_read_b128 v[214:217], v183 offset:59904
	ds_read_b128 v[218:221], v183 offset:59920
	ds_read_b64 v[234:235], v183 offset:59936
	s_waitcnt lgkmcnt(6)
	v_pk_mul_f32 v[150:151], v[142:143], v[190:191]
	v_pk_fma_f32 v[150:151], v[144:145], v[198:199], v[150:151]
	v_pk_mul_f32 v[152:153], v[142:143], v[236:237]
	v_add_f32_e32 v154, v150, v151
	v_pk_fma_f32 v[152:153], v[144:145], v[238:239], v[152:153]
	v_pk_mul_f32 v[146:147], v[142:143], v[192:193]
	v_add_f32_dpp v154, v154, v154 quad_perm:[1,0,3,2] row_mask:0xf bank_mask:0xf bound_ctrl:1
	v_pk_mul_f32 v[148:149], v[144:145], v[200:201]
	v_add_f32_e32 v161, v152, v153
	v_add_f32_dpp v154, v154, v154 quad_perm:[2,3,0,1] row_mask:0xf bank_mask:0xf bound_ctrl:1
	v_pk_fma_f32 v[146:147], v[242:243], v[196:197], v[146:147] op_sel:[0,0,0] op_sel_hi:[0,1,1]
	v_pk_fma_f32 v[148:149], v[242:243], v[204:205], v[148:149] op_sel:[0,0,0] op_sel_hi:[0,1,1]
	v_add_f32_dpp v154, v154, v154 row_half_mirror row_mask:0xf bank_mask:0xf bound_ctrl:1
	ds_read_b128 v[126:129], v182 offset:61440
	ds_read_b128 v[130:133], v182 offset:61456
	v_add_f32_dpp v154, v154, v154 row_mirror row_mask:0xf bank_mask:0xf bound_ctrl:1
	ds_read_b64 v[236:237], v182 offset:61472
	ds_read_b128 v[134:137], v183 offset:61440
	v_pk_fma_f32 v[146:147], v[154:155], v[194:195], v[146:147] op_sel_hi:[0,1,1]
	v_pk_fma_f32 v[148:149], v[154:155], v[202:203], v[148:149] op_sel_hi:[0,1,1]
	ds_read_b128 v[222:225], v183 offset:61456
	ds_read_b64 v[238:239], v183 offset:61472
	ds_read2_b32 v[240:241], v226 offset0:128 offset1:144
	s_waitcnt lgkmcnt(7)
	v_pk_mul_f32 v[150:151], v[146:147], v[206:207]
	v_pk_fma_f32 v[150:151], v[148:149], v[214:215], v[150:151]
	v_pk_mul_f32 v[152:153], v[146:147], v[228:229]
	v_add_f32_e32 v154, v150, v151
	v_pk_fma_f32 v[152:153], v[148:149], v[230:231], v[152:153]
	v_pk_mul_f32 v[142:143], v[146:147], v[208:209]
	v_add_f32_dpp v154, v154, v154 quad_perm:[1,0,3,2] row_mask:0xf bank_mask:0xf bound_ctrl:1
	v_pk_mul_f32 v[144:145], v[148:149], v[216:217]
	v_add_f32_e32 v162, v152, v153
	v_add_f32_dpp v154, v154, v154 quad_perm:[2,3,0,1] row_mask:0xf bank_mask:0xf bound_ctrl:1
	v_pk_fma_f32 v[142:143], v[242:243], v[212:213], v[142:143] op_sel:[1,0,0] op_sel_hi:[1,1,1]
	v_pk_fma_f32 v[144:145], v[242:243], v[220:221], v[144:145] op_sel:[1,0,0] op_sel_hi:[1,1,1]
	v_add_f32_dpp v154, v154, v154 row_half_mirror row_mask:0xf bank_mask:0xf bound_ctrl:1
	ds_read_b128 v[190:193], v182 offset:62976
	ds_read_b128 v[194:197], v182 offset:62992
	v_add_f32_dpp v154, v154, v154 row_mirror row_mask:0xf bank_mask:0xf bound_ctrl:1
	ds_read_b64 v[228:229], v182 offset:63008
	v_pk_fma_f32 v[142:143], v[154:155], v[210:211], v[142:143] op_sel_hi:[0,1,1]
	v_pk_fma_f32 v[144:145], v[154:155], v[218:219], v[144:145] op_sel_hi:[0,1,1]
	ds_read_b128 v[198:201], v183 offset:62976
	ds_read_b128 v[202:205], v183 offset:62992
	ds_read_b64 v[230:231], v183 offset:63008
	s_waitcnt lgkmcnt(6)
; __device__ __forceinline__ void wkv_phase(const WkvT& W, unsigned char* lds) {
;     ...
;                 for (int t = 0; t < 32; ++t) {
;                     const f32x2 a2 = {nA[0], nA[1]}, w2 = {nA[2], nA[3]}, b2 = {nB[0], nB[1]}, k2 = {nB[2], nB[3]}, r2 = nr; const float v = nv;
;                     if (t + 1 < 32) { nA = *(const f32x4*)(pp + (t + 1) * 384); nB = *(const f32x4*)(pp + (t + 1) * 384 + 4); nr = *(const f32x2*)(pp + (t + 1) * 384 + 8); nv = pv[(t + 1) * 16]; }
;                     float S0 = S.x, S1 = S.y;
;                     float d = S0 * a2.x; d = __builtin_fmaf(S1, a2.y, d);
;                     float t0 = S0 * w2.x; t0 = __builtin_fmaf(v, k2.x, t0); asm volatile("" : "+v"(t0));
;                     float t1 = S1 * w2.y; t1 = __builtin_fmaf(v, k2.y, t1); asm volatile("" : "+v"(t1));
;                     float yprev; const float sa = wkv_reduce(d, ep, yprev);
;                     S0 = __builtin_fmaf(sa, b2.x, t0); asm volatile("" : "+v"(S0));
;                     S1 = __builtin_fmaf(sa, b2.y, t1); asm volatile("" : "+v"(S1));
;                     ep = S0 * r2.x; ep = __builtin_fmaf(S1, r2.y, ep);
;                     S.x = S0; S.y = S1;
	v_pk_mul_f32 v[150:151], v[142:143], v[126:127]
	v_pk_fma_f32 v[150:151], v[144:145], v[134:135], v[150:151]
	v_pk_mul_f32 v[152:153], v[142:143], v[232:233]
	v_add_f32_e32 v154, v150, v151
	v_pk_fma_f32 v[152:153], v[144:145], v[234:235], v[152:153]
	v_pk_mul_f32 v[146:147], v[142:143], v[128:129]
	v_add_f32_dpp v154, v154, v154 quad_perm:[1,0,3,2] row_mask:0xf bank_mask:0xf bound_ctrl:1
	v_pk_mul_f32 v[148:149], v[144:145], v[136:137]
	v_add_f32_e32 v163, v152, v153
	v_add_f32_dpp v154, v154, v154 quad_perm:[2,3,0,1] row_mask:0xf bank_mask:0xf bound_ctrl:1
	v_pk_fma_f32 v[146:147], v[240:241], v[132:133], v[146:147] op_sel:[0,0,0] op_sel_hi:[0,1,1]
	v_pk_fma_f32 v[148:149], v[240:241], v[224:225], v[148:149] op_sel:[0,0,0] op_sel_hi:[0,1,1]
	v_add_f32_dpp v154, v154, v154 row_half_mirror row_mask:0xf bank_mask:0xf bound_ctrl:1
	ds_read_b128 v[206:209], v182 offset:64512
	ds_read_b128 v[210:213], v182 offset:64528
	v_add_f32_dpp v154, v154, v154 row_mirror row_mask:0xf bank_mask:0xf bound_ctrl:1
	ds_read_b64 v[232:233], v182 offset:64544
	ds_read_b128 v[214:217], v183 offset:64512
	v_pk_fma_f32 v[146:147], v[154:155], v[130:131], v[146:147] op_sel_hi:[0,1,1]
	v_pk_fma_f32 v[148:149], v[154:155], v[222:223], v[148:149] op_sel_hi:[0,1,1]
	ds_read_b128 v[218:221], v183 offset:64528
	ds_read_b64 v[234:235], v183 offset:64544
	ds_read2_b32 v[242:243], v226 offset0:160 offset1:176
	s_waitcnt lgkmcnt(7)
	v_pk_mul_f32 v[150:151], v[146:147], v[190:191]
	v_pk_fma_f32 v[150:151], v[148:149], v[198:199], v[150:151]
	v_pk_mul_f32 v[152:153], v[146:147], v[236:237]
	v_add_f32_e32 v154, v150, v151
	v_pk_fma_f32 v[152:153], v[148:149], v[238:239], v[152:153]
	v_pk_mul_f32 v[142:143], v[146:147], v[192:193]
	v_add_f32_dpp v154, v154, v154 quad_perm:[1,0,3,2] row_mask:0xf bank_mask:0xf bound_ctrl:1
	v_pk_mul_f32 v[144:145], v[148:149], v[200:201]
	v_add_f32_e32 v164, v152, v153
	v_add_f32_dpp v154, v154, v154 quad_perm:[2,3,0,1] row_mask:0xf bank_mask:0xf bound_ctrl:1
	v_pk_fma_f32 v[142:143], v[240:241], v[196:197], v[142:143] op_sel:[1,0,0] op_sel_hi:[1,1,1]
	v_pk_fma_f32 v[144:145], v[240:241], v[204:205], v[144:145] op_sel:[1,0,0] op_sel_hi:[1,1,1]
	v_add_f32_dpp v154, v154, v154 row_half_mirror row_mask:0xf bank_mask:0xf bound_ctrl:1
	ds_read_b128 v[126:129], v184
	ds_read_b128 v[130:133], v184 offset:16
	v_add_f32_dpp v154, v154, v154 row_mirror row_mask:0xf bank_mask:0xf bound_ctrl:1
	ds_read_b64 v[236:237], v184 offset:32
	v_pk_fma_f32 v[142:143], v[154:155], v[194:195], v[142:143] op_sel_hi:[0,1,1]
	v_pk_fma_f32 v[144:145], v[154:155], v[202:203], v[144:145] op_sel_hi:[0,1,1]
	ds_read_b128 v[134:137], v185
	ds_read_b128 v[222:225], v185 offset:16
	ds_read_b64 v[238:239], v185 offset:32
	s_waitcnt lgkmcnt(6)
	v_pk_mul_f32 v[150:151], v[142:143], v[206:207]
	v_pk_fma_f32 v[150:151], v[144:145], v[214:215], v[150:151]
	v_pk_mul_f32 v[152:153], v[142:143], v[228:229]
	v_add_f32_e32 v154, v150, v151
	v_pk_fma_f32 v[152:153], v[144:145], v[230:231], v[152:153]
	v_pk_mul_f32 v[146:147], v[142:143], v[208:209]
	v_add_f32_dpp v154, v154, v154 quad_perm:[1,0,3,2] row_mask:0xf bank_mask:0xf bound_ctrl:1
	v_pk_mul_f32 v[148:149], v[144:145], v[216:217]
	v_add_f32_e32 v165, v152, v153
	v_add_f32_dpp v154, v154, v154 quad_perm:[2,3,0,1] row_mask:0xf bank_mask:0xf bound_ctrl:1
	v_pk_fma_f32 v[146:147], v[242:243], v[212:213], v[146:147] op_sel:[0,0,0] op_sel_hi:[0,1,1]
	v_pk_fma_f32 v[148:149], v[242:243], v[220:221], v[148:149] op_sel:[0,0,0] op_sel_hi:[0,1,1]
	v_add_f32_dpp v154, v154, v154 row_half_mirror row_mask:0xf bank_mask:0xf bound_ctrl:1
	ds_read_b128 v[190:193], v184 offset:1536
	ds_read_b128 v[194:197], v184 offset:1552
	v_add_f32_dpp v154, v154, v154 row_mirror row_mask:0xf bank_mask:0xf bound_ctrl:1
	ds_read_b64 v[228:229], v184 offset:1568
	ds_read_b128 v[198:201], v185 offset:1536
	v_pk_fma_f32 v[146:147], v[154:155], v[210:211], v[146:147] op_sel_hi:[0,1,1]
	v_pk_fma_f32 v[148:149], v[154:155], v[218:219], v[148:149] op_sel_hi:[0,1,1]
	ds_read_b128 v[202:205], v185 offset:1552
	ds_read_b64 v[230:231], v185 offset:1568
	ds_read2_b32 v[240:241], v226 offset0:192 offset1:208
	s_waitcnt lgkmcnt(7)
	v_pk_mul_f32 v[150:151], v[146:147], v[126:127]
	v_pk_fma_f32 v[150:151], v[148:149], v[134:135], v[150:151]
	v_pk_mul_f32 v[152:153], v[146:147], v[232:233]
	v_add_f32_e32 v154, v150, v151
	v_pk_fma_f32 v[152:153], v[148:149], v[234:235], v[152:153]
	v_pk_mul_f32 v[142:143], v[146:147], v[128:129]
	v_add_f32_dpp v154, v154, v154 quad_perm:[1,0,3,2] row_mask:0xf bank_mask:0xf bound_ctrl:1
	v_pk_mul_f32 v[144:145], v[148:149], v[136:137]
	v_add_f32_e32 v166, v152, v153
	v_add_f32_dpp v154, v154, v154 quad_perm:[2,3,0,1] row_mask:0xf bank_mask:0xf bound_ctrl:1
	v_pk_fma_f32 v[142:143], v[242:243], v[132:133], v[142:143] op_sel:[1,0,0] op_sel_hi:[1,1,1]
	v_pk_fma_f32 v[144:145], v[242:243], v[224:225], v[144:145] op_sel:[1,0,0] op_sel_hi:[1,1,1]
	v_add_f32_dpp v154, v154, v154 row_half_mirror row_mask:0xf bank_mask:0xf bound_ctrl:1
	ds_read_b128 v[206:209], v184 offset:3072
	ds_read_b128 v[210:213], v184 offset:3088
	v_add_f32_dpp v154, v154, v154 row_mirror row_mask:0xf bank_mask:0xf bound_ctrl:1
	ds_read_b64 v[232:233], v184 offset:3104
	v_pk_fma_f32 v[142:143], v[154:155], v[130:131], v[142:143] op_sel_hi:[0,1,1]
	v_pk_fma_f32 v[144:145], v[154:155], v[222:223], v[144:145] op_sel_hi:[0,1,1]
	ds_read_b128 v[214:217], v185 offset:3072
	ds_read_b128 v[218:221], v185 offset:3088
	ds_read_b64 v[234:235], v185 offset:3104
	s_waitcnt lgkmcnt(6)
; __device__ __forceinline__ void wkv_phase(const WkvT& W, unsigned char* lds) {
;     ...
;                 for (int t = 0; t < 32; ++t) {
;                     const f32x2 a2 = {nA[0], nA[1]}, w2 = {nA[2], nA[3]}, b2 = {nB[0], nB[1]}, k2 = {nB[2], nB[3]}, r2 = nr; const float v = nv;
;                     if (t + 1 < 32) { nA = *(const f32x4*)(pp + (t + 1) * 384); nB = *(const f32x4*)(pp + (t + 1) * 384 + 4); nr = *(const f32x2*)(pp + (t + 1) * 384 + 8); nv = pv[(t + 1) * 16]; }
;                     float S0 = S.x, S1 = S.y;
;                     float d = S0 * a2.x; d = __builtin_fmaf(S1, a2.y, d);
;                     float t0 = S0 * w2.x; t0 = __builtin_fmaf(v, k2.x, t0); asm volatile("" : "+v"(t0));
;                     float t1 = S1 * w2.y; t1 = __builtin_fmaf(v, k2.y, t1); asm volatile("" : "+v"(t1));
;                     float yprev; const float sa = wkv_reduce(d, ep, yprev);
;                     S0 = __builtin_fmaf(sa, b2.x, t0); asm volatile("" : "+v"(S0));
;                     S1 = __builtin_fmaf(sa, b2.y, t1); asm volatile("" : "+v"(S1));
;                     ep = S0 * r2.x; ep = __builtin_fmaf(S1, r2.y, ep);
;                     S.x = S0; S.y = S1;
	v_pk_mul_f32 v[150:151], v[142:143], v[190:191]
	v_pk_fma_f32 v[150:151], v[144:145], v[198:199], v[150:151]
	v_pk_mul_f32 v[152:153], v[142:143], v[236:237]
	v_add_f32_e32 v154, v150, v151
	v_pk_fma_f32 v[152:153], v[144:145], v[238:239], v[152:153]
	v_pk_mul_f32 v[146:147], v[142:143], v[192:193]
	v_add_f32_dpp v154, v154, v154 quad_perm:[1,0,3,2] row_mask:0xf bank_mask:0xf bound_ctrl:1
	v_pk_mul_f32 v[148:149], v[144:145], v[200:201]
	v_add_f32_e32 v167, v152, v153
	v_add_f32_dpp v154, v154, v154 quad_perm:[2,3,0,1] row_mask:0xf bank_mask:0xf bound_ctrl:1
	v_pk_fma_f32 v[146:147], v[240:241], v[196:197], v[146:147] op_sel:[0,0,0] op_sel_hi:[0,1,1]
	v_pk_fma_f32 v[148:149], v[240:241], v[204:205], v[148:149] op_sel:[0,0,0] op_sel_hi:[0,1,1]
	v_add_f32_dpp v154, v154, v154 row_half_mirror row_mask:0xf bank_mask:0xf bound_ctrl:1
	ds_read_b128 v[126:129], v184 offset:4608
	ds_read_b128 v[130:133], v184 offset:4624
	v_add_f32_dpp v154, v154, v154 row_mirror row_mask:0xf bank_mask:0xf bound_ctrl:1
	ds_read_b64 v[236:237], v184 offset:4640
	ds_read_b128 v[134:137], v185 offset:4608
	v_pk_fma_f32 v[146:147], v[154:155], v[194:195], v[146:147] op_sel_hi:[0,1,1]
	v_pk_fma_f32 v[148:149], v[154:155], v[202:203], v[148:149] op_sel_hi:[0,1,1]
	ds_read_b128 v[222:225], v185 offset:4624
	ds_read_b64 v[238:239], v185 offset:4640
	ds_read2_b32 v[242:243], v226 offset0:224 offset1:240
	s_waitcnt lgkmcnt(7)
	v_pk_mul_f32 v[150:151], v[146:147], v[206:207]
	v_pk_fma_f32 v[150:151], v[148:149], v[214:215], v[150:151]
	v_pk_mul_f32 v[152:153], v[146:147], v[228:229]
	v_add_f32_e32 v154, v150, v151
	v_pk_fma_f32 v[152:153], v[148:149], v[230:231], v[152:153]
	v_pk_mul_f32 v[142:143], v[146:147], v[208:209]
	v_add_f32_dpp v154, v154, v154 quad_perm:[1,0,3,2] row_mask:0xf bank_mask:0xf bound_ctrl:1
	v_pk_mul_f32 v[144:145], v[148:149], v[216:217]
	v_add_f32_e32 v168, v152, v153
	v_add_f32_dpp v154, v154, v154 quad_perm:[2,3,0,1] row_mask:0xf bank_mask:0xf bound_ctrl:1
	v_pk_fma_f32 v[142:143], v[240:241], v[212:213], v[142:143] op_sel:[1,0,0] op_sel_hi:[1,1,1]
	v_pk_fma_f32 v[144:145], v[240:241], v[220:221], v[144:145] op_sel:[1,0,0] op_sel_hi:[1,1,1]
	v_add_f32_dpp v154, v154, v154 row_half_mirror row_mask:0xf bank_mask:0xf bound_ctrl:1
	ds_read_b128 v[190:193], v184 offset:6144
	ds_read_b128 v[194:197], v184 offset:6160
	v_add_f32_dpp v154, v154, v154 row_mirror row_mask:0xf bank_mask:0xf bound_ctrl:1
	ds_read_b64 v[228:229], v184 offset:6176
	v_pk_fma_f32 v[142:143], v[154:155], v[210:211], v[142:143] op_sel_hi:[0,1,1]
	v_pk_fma_f32 v[144:145], v[154:155], v[218:219], v[144:145] op_sel_hi:[0,1,1]
	ds_read_b128 v[198:201], v185 offset:6144
	ds_read_b128 v[202:205], v185 offset:6160
	ds_read_b64 v[230:231], v185 offset:6176
	s_waitcnt lgkmcnt(6)
	v_pk_mul_f32 v[150:151], v[142:143], v[126:127]
	v_pk_fma_f32 v[150:151], v[144:145], v[134:135], v[150:151]
	v_pk_mul_f32 v[152:153], v[142:143], v[232:233]
	v_add_f32_e32 v154, v150, v151
	v_pk_fma_f32 v[152:153], v[144:145], v[234:235], v[152:153]
	v_pk_mul_f32 v[146:147], v[142:143], v[128:129]
	v_add_f32_dpp v154, v154, v154 quad_perm:[1,0,3,2] row_mask:0xf bank_mask:0xf bound_ctrl:1
	v_pk_mul_f32 v[148:149], v[144:145], v[136:137]
	v_add_f32_e32 v169, v152, v153
	v_add_f32_dpp v154, v154, v154 quad_perm:[2,3,0,1] row_mask:0xf bank_mask:0xf bound_ctrl:1
	v_pk_fma_f32 v[146:147], v[242:243], v[132:133], v[146:147] op_sel:[0,0,0] op_sel_hi:[0,1,1]
	v_pk_fma_f32 v[148:149], v[242:243], v[224:225], v[148:149] op_sel:[0,0,0] op_sel_hi:[0,1,1]
	v_add_f32_dpp v154, v154, v154 row_half_mirror row_mask:0xf bank_mask:0xf bound_ctrl:1
	ds_read_b128 v[206:209], v184 offset:7680
	ds_read_b128 v[210:213], v184 offset:7696
	v_add_f32_dpp v154, v154, v154 row_mirror row_mask:0xf bank_mask:0xf bound_ctrl:1
	ds_read_b64 v[232:233], v184 offset:7712
	ds_read_b128 v[214:217], v185 offset:7680
	v_pk_fma_f32 v[146:147], v[154:155], v[130:131], v[146:147] op_sel_hi:[0,1,1]
	v_pk_fma_f32 v[148:149], v[154:155], v[222:223], v[148:149] op_sel_hi:[0,1,1]
	ds_read_b128 v[218:221], v185 offset:7696
	ds_read_b64 v[234:235], v185 offset:7712
	ds_read2_b32 v[240:241], v227 offset0:0 offset1:16
	s_waitcnt lgkmcnt(7)
	v_pk_mul_f32 v[150:151], v[146:147], v[190:191]
	v_pk_fma_f32 v[150:151], v[148:149], v[198:199], v[150:151]
	v_pk_mul_f32 v[152:153], v[146:147], v[236:237]
	v_add_f32_e32 v154, v150, v151
	v_pk_fma_f32 v[152:153], v[148:149], v[238:239], v[152:153]
	v_pk_mul_f32 v[142:143], v[146:147], v[192:193]
	v_add_f32_dpp v154, v154, v154 quad_perm:[1,0,3,2] row_mask:0xf bank_mask:0xf bound_ctrl:1
	v_pk_mul_f32 v[144:145], v[148:149], v[200:201]
	v_add_f32_e32 v170, v152, v153
	v_add_f32_dpp v154, v154, v154 quad_perm:[2,3,0,1] row_mask:0xf bank_mask:0xf bound_ctrl:1
	v_pk_fma_f32 v[142:143], v[242:243], v[196:197], v[142:143] op_sel:[1,0,0] op_sel_hi:[1,1,1]
	v_pk_fma_f32 v[144:145], v[242:243], v[204:205], v[144:145] op_sel:[1,0,0] op_sel_hi:[1,1,1]
	v_add_f32_dpp v154, v154, v154 row_half_mirror row_mask:0xf bank_mask:0xf bound_ctrl:1
	ds_read_b128 v[126:129], v184 offset:9216
	ds_read_b128 v[130:133], v184 offset:9232
	v_add_f32_dpp v154, v154, v154 row_mirror row_mask:0xf bank_mask:0xf bound_ctrl:1
	ds_read_b64 v[236:237], v184 offset:9248
	v_pk_fma_f32 v[142:143], v[154:155], v[194:195], v[142:143] op_sel_hi:[0,1,1]
	v_pk_fma_f32 v[144:145], v[154:155], v[202:203], v[144:145] op_sel_hi:[0,1,1]
	ds_read_b128 v[134:137], v185 offset:9216
	ds_read_b128 v[222:225], v185 offset:9232
	ds_read_b64 v[238:239], v185 offset:9248
	s_waitcnt lgkmcnt(6)
; __device__ __forceinline__ void wkv_phase(const WkvT& W, unsigned char* lds) {
;     ...
;                 for (int t = 0; t < 32; ++t) {
;                     const f32x2 a2 = {nA[0], nA[1]}, w2 = {nA[2], nA[3]}, b2 = {nB[0], nB[1]}, k2 = {nB[2], nB[3]}, r2 = nr; const float v = nv;
;                     if (t + 1 < 32) { nA = *(const f32x4*)(pp + (t + 1) * 384); nB = *(const f32x4*)(pp + (t + 1) * 384 + 4); nr = *(const f32x2*)(pp + (t + 1) * 384 + 8); nv = pv[(t + 1) * 16]; }
;                     float S0 = S.x, S1 = S.y;
;                     float d = S0 * a2.x; d = __builtin_fmaf(S1, a2.y, d);
;                     float t0 = S0 * w2.x; t0 = __builtin_fmaf(v, k2.x, t0); asm volatile("" : "+v"(t0));
;                     float t1 = S1 * w2.y; t1 = __builtin_fmaf(v, k2.y, t1); asm volatile("" : "+v"(t1));
;                     float yprev; const float sa = wkv_reduce(d, ep, yprev);
;                     S0 = __builtin_fmaf(sa, b2.x, t0); asm volatile("" : "+v"(S0));
;                     S1 = __builtin_fmaf(sa, b2.y, t1); asm volatile("" : "+v"(S1));
;                     ep = S0 * r2.x; ep = __builtin_fmaf(S1, r2.y, ep);
;                     S.x = S0; S.y = S1;
;                     if (t >= 1) { const bool hit = oddrow && ((lane & 15) == ((t - 1) & 15)); if (t <= 16) yk0 = hit ? yprev : yk0; else yk1 = hit ? yprev : yk1; }
;                 }
;                 { float ylast; (void)wkv_reduce(0.f, ep, ylast); yk1 = (oddrow && (lane & 15) == 15) ? ylast : yk1; }
;                 if (oddrow) { sY[bi * 512 + (lane & 15) * 16 + il] = yk0; sY[bi * 512 + (16 + (lane & 15)) * 16 + il] = yk1; }
	v_pk_mul_f32 v[150:151], v[142:143], v[206:207]
	v_pk_fma_f32 v[150:151], v[144:145], v[214:215], v[150:151]
	v_pk_mul_f32 v[152:153], v[142:143], v[228:229]
	v_add_f32_e32 v154, v150, v151
	v_pk_fma_f32 v[152:153], v[144:145], v[230:231], v[152:153]
	v_pk_mul_f32 v[146:147], v[142:143], v[208:209]
	v_add_f32_dpp v154, v154, v154 quad_perm:[1,0,3,2] row_mask:0xf bank_mask:0xf bound_ctrl:1
	v_pk_mul_f32 v[148:149], v[144:145], v[216:217]
	v_add_f32_e32 v171, v152, v153
	v_add_f32_dpp v154, v154, v154 quad_perm:[2,3,0,1] row_mask:0xf bank_mask:0xf bound_ctrl:1
	v_pk_fma_f32 v[146:147], v[240:241], v[212:213], v[146:147] op_sel:[0,0,0] op_sel_hi:[0,1,1]
	v_pk_fma_f32 v[148:149], v[240:241], v[220:221], v[148:149] op_sel:[0,0,0] op_sel_hi:[0,1,1]
	v_add_f32_dpp v154, v154, v154 row_half_mirror row_mask:0xf bank_mask:0xf bound_ctrl:1
	ds_read_b128 v[190:193], v184 offset:10752
	ds_read_b128 v[194:197], v184 offset:10768
	v_add_f32_dpp v154, v154, v154 row_mirror row_mask:0xf bank_mask:0xf bound_ctrl:1
	ds_read_b64 v[228:229], v184 offset:10784
	ds_read_b128 v[198:201], v185 offset:10752
	v_pk_fma_f32 v[146:147], v[154:155], v[210:211], v[146:147] op_sel_hi:[0,1,1]
	v_pk_fma_f32 v[148:149], v[154:155], v[218:219], v[148:149] op_sel_hi:[0,1,1]
	ds_read_b128 v[202:205], v185 offset:10768
	ds_read_b64 v[230:231], v185 offset:10784
	ds_read2_b32 v[242:243], v227 offset0:32 offset1:48
	s_waitcnt lgkmcnt(7)
	v_add_f32_dpp v172, v156, v156 row_ror:8 row_mask:0xf bank_mask:0x3
	v_add_f32_dpp v173, v157, v157 row_ror:8 row_mask:0xf bank_mask:0x3
	v_add_f32_dpp v174, v158, v158 row_ror:8 row_mask:0xf bank_mask:0x3
	v_add_f32_dpp v175, v159, v159 row_ror:8 row_mask:0xf bank_mask:0x3
	v_add_f32_dpp v176, v160, v160 row_ror:8 row_mask:0xf bank_mask:0x3
	v_add_f32_dpp v177, v161, v161 row_ror:8 row_mask:0xf bank_mask:0x3
	v_add_f32_dpp v178, v162, v162 row_ror:8 row_mask:0xf bank_mask:0x3
	v_add_f32_dpp v179, v163, v163 row_ror:8 row_mask:0xf bank_mask:0x3
	v_add_f32_dpp v172, v164, v164 row_ror:8 row_mask:0xf bank_mask:0xc
	v_add_f32_dpp v173, v165, v165 row_ror:8 row_mask:0xf bank_mask:0xc
	v_add_f32_dpp v174, v166, v166 row_ror:8 row_mask:0xf bank_mask:0xc
	v_add_f32_dpp v175, v167, v167 row_ror:8 row_mask:0xf bank_mask:0xc
	v_add_f32_dpp v176, v168, v168 row_ror:8 row_mask:0xf bank_mask:0xc
	v_add_f32_dpp v177, v169, v169 row_ror:8 row_mask:0xf bank_mask:0xc
	v_add_f32_dpp v178, v170, v170 row_ror:8 row_mask:0xf bank_mask:0xc
	v_add_f32_dpp v179, v171, v171 row_ror:8 row_mask:0xf bank_mask:0xc
	v_add_f32_dpp v156, v172, v172 row_half_mirror row_mask:0xf bank_mask:0x5
	v_add_f32_dpp v157, v173, v173 row_half_mirror row_mask:0xf bank_mask:0x5
	v_add_f32_dpp v158, v174, v174 row_half_mirror row_mask:0xf bank_mask:0x5
	v_add_f32_dpp v159, v175, v175 row_half_mirror row_mask:0xf bank_mask:0x5
	v_add_f32_dpp v156, v176, v176 row_half_mirror row_mask:0xf bank_mask:0xa
	v_add_f32_dpp v157, v177, v177 row_half_mirror row_mask:0xf bank_mask:0xa
	v_add_f32_dpp v158, v178, v178 row_half_mirror row_mask:0xf bank_mask:0xa
	v_add_f32_dpp v159, v179, v179 row_half_mirror row_mask:0xf bank_mask:0xa
	v_cndmask_b32_e64 v178, v156, v158, s[14:15]
	v_cndmask_b32_e64 v176, v158, v156, s[14:15]
	v_cndmask_b32_e64 v179, v157, v159, s[14:15]
	v_cndmask_b32_e64 v177, v159, v157, s[14:15]
	s_nop 1
	v_add_f32_dpp v172, v176, v178 quad_perm:[2,3,0,1] row_mask:0xf bank_mask:0xf
	v_add_f32_dpp v173, v177, v179 quad_perm:[2,3,0,1] row_mask:0xf bank_mask:0xf
	v_cndmask_b32_e64 v176, v173, v172, s[16:17]
	v_cndmask_b32_e64 v178, v172, v173, s[16:17]
	s_nop 1
	v_add_f32_dpp v180, v176, v178 quad_perm:[1,0,3,2] row_mask:0xf bank_mask:0xf
	v_pk_mul_f32 v[150:151], v[146:147], v[126:127]
	v_pk_fma_f32 v[150:151], v[148:149], v[134:135], v[150:151]
	v_pk_mul_f32 v[152:153], v[146:147], v[232:233]
	v_add_f32_e32 v154, v150, v151
	v_pk_fma_f32 v[152:153], v[148:149], v[234:235], v[152:153]
	v_pk_mul_f32 v[142:143], v[146:147], v[128:129]
	v_add_f32_dpp v154, v154, v154 quad_perm:[1,0,3,2] row_mask:0xf bank_mask:0xf bound_ctrl:1
	v_pk_mul_f32 v[144:145], v[148:149], v[136:137]
	v_add_f32_e32 v156, v152, v153
	v_add_f32_dpp v154, v154, v154 quad_perm:[2,3,0,1] row_mask:0xf bank_mask:0xf bound_ctrl:1
	v_pk_fma_f32 v[142:143], v[240:241], v[132:133], v[142:143] op_sel:[1,0,0] op_sel_hi:[1,1,1]
	v_pk_fma_f32 v[144:145], v[240:241], v[224:225], v[144:145] op_sel:[1,0,0] op_sel_hi:[1,1,1]
	v_add_f32_dpp v154, v154, v154 row_half_mirror row_mask:0xf bank_mask:0xf bound_ctrl:1
	ds_read_b128 v[206:209], v184 offset:12288
	ds_read_b128 v[210:213], v184 offset:12304
	v_add_f32_dpp v154, v154, v154 row_mirror row_mask:0xf bank_mask:0xf bound_ctrl:1
	ds_read_b64 v[232:233], v184 offset:12320
	v_pk_fma_f32 v[142:143], v[154:155], v[130:131], v[142:143] op_sel_hi:[0,1,1]
	v_pk_fma_f32 v[144:145], v[154:155], v[222:223], v[144:145] op_sel_hi:[0,1,1]
	ds_read_b128 v[214:217], v185 offset:12288
	ds_read_b128 v[218:221], v185 offset:12304
	ds_read_b64 v[234:235], v185 offset:12320
	s_waitcnt lgkmcnt(6)
; __device__ __forceinline__ void wkv_phase(const WkvT& W, unsigned char* lds) {
;     ...
;                 for (int t = 0; t < 32; ++t) {
;                     const f32x2 a2 = {nA[0], nA[1]}, w2 = {nA[2], nA[3]}, b2 = {nB[0], nB[1]}, k2 = {nB[2], nB[3]}, r2 = nr; const float v = nv;
;                     if (t + 1 < 32) { nA = *(const f32x4*)(pp + (t + 1) * 384); nB = *(const f32x4*)(pp + (t + 1) * 384 + 4); nr = *(const f32x2*)(pp + (t + 1) * 384 + 8); nv = pv[(t + 1) * 16]; }
;                     float S0 = S.x, S1 = S.y;
;                     float d = S0 * a2.x; d = __builtin_fmaf(S1, a2.y, d);
;                     float t0 = S0 * w2.x; t0 = __builtin_fmaf(v, k2.x, t0); asm volatile("" : "+v"(t0));
;                     float t1 = S1 * w2.y; t1 = __builtin_fmaf(v, k2.y, t1); asm volatile("" : "+v"(t1));
;                     float yprev; const float sa = wkv_reduce(d, ep, yprev);
;                     S0 = __builtin_fmaf(sa, b2.x, t0); asm volatile("" : "+v"(S0));
;                     S1 = __builtin_fmaf(sa, b2.y, t1); asm volatile("" : "+v"(S1));
;                     ep = S0 * r2.x; ep = __builtin_fmaf(S1, r2.y, ep);
;                     S.x = S0; S.y = S1;
	v_pk_mul_f32 v[150:151], v[142:143], v[190:191]
	v_pk_fma_f32 v[150:151], v[144:145], v[198:199], v[150:151]
	v_pk_mul_f32 v[152:153], v[142:143], v[236:237]
	v_add_f32_e32 v154, v150, v151
	v_pk_fma_f32 v[152:153], v[144:145], v[238:239], v[152:153]
	v_pk_mul_f32 v[146:147], v[142:143], v[192:193]
	v_add_f32_dpp v154, v154, v154 quad_perm:[1,0,3,2] row_mask:0xf bank_mask:0xf bound_ctrl:1
	v_pk_mul_f32 v[148:149], v[144:145], v[200:201]
	v_add_f32_e32 v157, v152, v153
	v_add_f32_dpp v154, v154, v154 quad_perm:[2,3,0,1] row_mask:0xf bank_mask:0xf bound_ctrl:1
	v_pk_fma_f32 v[146:147], v[242:243], v[196:197], v[146:147] op_sel:[0,0,0] op_sel_hi:[0,1,1]
	v_pk_fma_f32 v[148:149], v[242:243], v[204:205], v[148:149] op_sel:[0,0,0] op_sel_hi:[0,1,1]
	v_add_f32_dpp v154, v154, v154 row_half_mirror row_mask:0xf bank_mask:0xf bound_ctrl:1
	ds_read_b128 v[126:129], v184 offset:13824
	ds_read_b128 v[130:133], v184 offset:13840
	v_add_f32_dpp v154, v154, v154 row_mirror row_mask:0xf bank_mask:0xf bound_ctrl:1
	ds_read_b64 v[236:237], v184 offset:13856
	ds_read_b128 v[134:137], v185 offset:13824
	v_pk_fma_f32 v[146:147], v[154:155], v[194:195], v[146:147] op_sel_hi:[0,1,1]
	v_pk_fma_f32 v[148:149], v[154:155], v[202:203], v[148:149] op_sel_hi:[0,1,1]
	ds_read_b128 v[222:225], v185 offset:13840
	ds_read_b64 v[238:239], v185 offset:13856
	ds_read2_b32 v[240:241], v227 offset0:64 offset1:80
	s_waitcnt lgkmcnt(7)
	v_pk_mul_f32 v[150:151], v[146:147], v[206:207]
	v_pk_fma_f32 v[150:151], v[148:149], v[214:215], v[150:151]
	v_pk_mul_f32 v[152:153], v[146:147], v[228:229]
	v_add_f32_e32 v154, v150, v151
	v_pk_fma_f32 v[152:153], v[148:149], v[230:231], v[152:153]
	v_pk_mul_f32 v[142:143], v[146:147], v[208:209]
	v_add_f32_dpp v154, v154, v154 quad_perm:[1,0,3,2] row_mask:0xf bank_mask:0xf bound_ctrl:1
	v_pk_mul_f32 v[144:145], v[148:149], v[216:217]
	v_add_f32_e32 v158, v152, v153
	v_add_f32_dpp v154, v154, v154 quad_perm:[2,3,0,1] row_mask:0xf bank_mask:0xf bound_ctrl:1
	v_pk_fma_f32 v[142:143], v[242:243], v[212:213], v[142:143] op_sel:[1,0,0] op_sel_hi:[1,1,1]
	v_pk_fma_f32 v[144:145], v[242:243], v[220:221], v[144:145] op_sel:[1,0,0] op_sel_hi:[1,1,1]
	v_add_f32_dpp v154, v154, v154 row_half_mirror row_mask:0xf bank_mask:0xf bound_ctrl:1
	ds_read_b128 v[190:193], v184 offset:15360
	ds_read_b128 v[194:197], v184 offset:15376
	v_add_f32_dpp v154, v154, v154 row_mirror row_mask:0xf bank_mask:0xf bound_ctrl:1
	ds_read_b64 v[228:229], v184 offset:15392
	v_pk_fma_f32 v[142:143], v[154:155], v[210:211], v[142:143] op_sel_hi:[0,1,1]
	v_pk_fma_f32 v[144:145], v[154:155], v[218:219], v[144:145] op_sel_hi:[0,1,1]
	ds_read_b128 v[198:201], v185 offset:15360
	ds_read_b128 v[202:205], v185 offset:15376
	ds_read_b64 v[230:231], v185 offset:15392
	s_waitcnt lgkmcnt(6)
	v_pk_mul_f32 v[150:151], v[142:143], v[126:127]
	v_pk_fma_f32 v[150:151], v[144:145], v[134:135], v[150:151]
	v_pk_mul_f32 v[152:153], v[142:143], v[232:233]
	v_add_f32_e32 v154, v150, v151
	v_pk_fma_f32 v[152:153], v[144:145], v[234:235], v[152:153]
	v_pk_mul_f32 v[146:147], v[142:143], v[128:129]
	v_add_f32_dpp v154, v154, v154 quad_perm:[1,0,3,2] row_mask:0xf bank_mask:0xf bound_ctrl:1
	v_pk_mul_f32 v[148:149], v[144:145], v[136:137]
	v_add_f32_e32 v159, v152, v153
	v_add_f32_dpp v154, v154, v154 quad_perm:[2,3,0,1] row_mask:0xf bank_mask:0xf bound_ctrl:1
	v_pk_fma_f32 v[146:147], v[240:241], v[132:133], v[146:147] op_sel:[0,0,0] op_sel_hi:[0,1,1]
	v_pk_fma_f32 v[148:149], v[240:241], v[224:225], v[148:149] op_sel:[0,0,0] op_sel_hi:[0,1,1]
	v_add_f32_dpp v154, v154, v154 row_half_mirror row_mask:0xf bank_mask:0xf bound_ctrl:1
	ds_read_b128 v[206:209], v184 offset:16896
	ds_read_b128 v[210:213], v184 offset:16912
	v_add_f32_dpp v154, v154, v154 row_mirror row_mask:0xf bank_mask:0xf bound_ctrl:1
	ds_read_b64 v[232:233], v184 offset:16928
	ds_read_b128 v[214:217], v185 offset:16896
	v_pk_fma_f32 v[146:147], v[154:155], v[130:131], v[146:147] op_sel_hi:[0,1,1]
	v_pk_fma_f32 v[148:149], v[154:155], v[222:223], v[148:149] op_sel_hi:[0,1,1]
	ds_read_b128 v[218:221], v185 offset:16912
	ds_read_b64 v[234:235], v185 offset:16928
	ds_read2_b32 v[242:243], v227 offset0:96 offset1:112
	s_waitcnt lgkmcnt(7)
	v_pk_mul_f32 v[150:151], v[146:147], v[190:191]
	v_pk_fma_f32 v[150:151], v[148:149], v[198:199], v[150:151]
	v_pk_mul_f32 v[152:153], v[146:147], v[236:237]
	v_add_f32_e32 v154, v150, v151
	v_pk_fma_f32 v[152:153], v[148:149], v[238:239], v[152:153]
	v_pk_mul_f32 v[142:143], v[146:147], v[192:193]
	v_add_f32_dpp v154, v154, v154 quad_perm:[1,0,3,2] row_mask:0xf bank_mask:0xf bound_ctrl:1
	v_pk_mul_f32 v[144:145], v[148:149], v[200:201]
	v_add_f32_e32 v160, v152, v153
	v_add_f32_dpp v154, v154, v154 quad_perm:[2,3,0,1] row_mask:0xf bank_mask:0xf bound_ctrl:1
	v_pk_fma_f32 v[142:143], v[240:241], v[196:197], v[142:143] op_sel:[1,0,0] op_sel_hi:[1,1,1]
	v_pk_fma_f32 v[144:145], v[240:241], v[204:205], v[144:145] op_sel:[1,0,0] op_sel_hi:[1,1,1]
	v_add_f32_dpp v154, v154, v154 row_half_mirror row_mask:0xf bank_mask:0xf bound_ctrl:1
	ds_read_b128 v[126:129], v184 offset:18432
	ds_read_b128 v[130:133], v184 offset:18448
	v_add_f32_dpp v154, v154, v154 row_mirror row_mask:0xf bank_mask:0xf bound_ctrl:1
	ds_read_b64 v[236:237], v184 offset:18464
	v_pk_fma_f32 v[142:143], v[154:155], v[194:195], v[142:143] op_sel_hi:[0,1,1]
	v_pk_fma_f32 v[144:145], v[154:155], v[202:203], v[144:145] op_sel_hi:[0,1,1]
	ds_read_b128 v[134:137], v185 offset:18432
	ds_read_b128 v[222:225], v185 offset:18448
	ds_read_b64 v[238:239], v185 offset:18464
	s_waitcnt lgkmcnt(6)
; __device__ __forceinline__ void wkv_phase(const WkvT& W, unsigned char* lds) {
;     ...
;                 for (int t = 0; t < 32; ++t) {
;                     const f32x2 a2 = {nA[0], nA[1]}, w2 = {nA[2], nA[3]}, b2 = {nB[0], nB[1]}, k2 = {nB[2], nB[3]}, r2 = nr; const float v = nv;
;                     if (t + 1 < 32) { nA = *(const f32x4*)(pp + (t + 1) * 384); nB = *(const f32x4*)(pp + (t + 1) * 384 + 4); nr = *(const f32x2*)(pp + (t + 1) * 384 + 8); nv = pv[(t + 1) * 16]; }
;                     float S0 = S.x, S1 = S.y;
;                     float d = S0 * a2.x; d = __builtin_fmaf(S1, a2.y, d);
;                     float t0 = S0 * w2.x; t0 = __builtin_fmaf(v, k2.x, t0); asm volatile("" : "+v"(t0));
;                     float t1 = S1 * w2.y; t1 = __builtin_fmaf(v, k2.y, t1); asm volatile("" : "+v"(t1));
;                     float yprev; const float sa = wkv_reduce(d, ep, yprev);
;                     S0 = __builtin_fmaf(sa, b2.x, t0); asm volatile("" : "+v"(S0));
;                     S1 = __builtin_fmaf(sa, b2.y, t1); asm volatile("" : "+v"(S1));
;                     ep = S0 * r2.x; ep = __builtin_fmaf(S1, r2.y, ep);
;                     S.x = S0; S.y = S1;
	v_pk_mul_f32 v[150:151], v[142:143], v[206:207]
	v_pk_fma_f32 v[150:151], v[144:145], v[214:215], v[150:151]
	v_pk_mul_f32 v[152:153], v[142:143], v[228:229]
	v_add_f32_e32 v154, v150, v151
	v_pk_fma_f32 v[152:153], v[144:145], v[230:231], v[152:153]
	v_pk_mul_f32 v[146:147], v[142:143], v[208:209]
	v_add_f32_dpp v154, v154, v154 quad_perm:[1,0,3,2] row_mask:0xf bank_mask:0xf bound_ctrl:1
	v_pk_mul_f32 v[148:149], v[144:145], v[216:217]
	v_add_f32_e32 v161, v152, v153
	v_add_f32_dpp v154, v154, v154 quad_perm:[2,3,0,1] row_mask:0xf bank_mask:0xf bound_ctrl:1
	v_pk_fma_f32 v[146:147], v[242:243], v[212:213], v[146:147] op_sel:[0,0,0] op_sel_hi:[0,1,1]
	v_pk_fma_f32 v[148:149], v[242:243], v[220:221], v[148:149] op_sel:[0,0,0] op_sel_hi:[0,1,1]
	v_add_f32_dpp v154, v154, v154 row_half_mirror row_mask:0xf bank_mask:0xf bound_ctrl:1
	ds_read_b128 v[190:193], v184 offset:19968
	ds_read_b128 v[194:197], v184 offset:19984
	v_add_f32_dpp v154, v154, v154 row_mirror row_mask:0xf bank_mask:0xf bound_ctrl:1
	ds_read_b64 v[228:229], v184 offset:20000
	ds_read_b128 v[198:201], v185 offset:19968
	v_pk_fma_f32 v[146:147], v[154:155], v[210:211], v[146:147] op_sel_hi:[0,1,1]
	v_pk_fma_f32 v[148:149], v[154:155], v[218:219], v[148:149] op_sel_hi:[0,1,1]
	ds_read_b128 v[202:205], v185 offset:19984
	ds_read_b64 v[230:231], v185 offset:20000
	ds_read2_b32 v[240:241], v227 offset0:128 offset1:144
	s_waitcnt lgkmcnt(7)
	v_pk_mul_f32 v[150:151], v[146:147], v[126:127]
	v_pk_fma_f32 v[150:151], v[148:149], v[134:135], v[150:151]
	v_pk_mul_f32 v[152:153], v[146:147], v[232:233]
	v_add_f32_e32 v154, v150, v151
	v_pk_fma_f32 v[152:153], v[148:149], v[234:235], v[152:153]
	v_pk_mul_f32 v[142:143], v[146:147], v[128:129]
	v_add_f32_dpp v154, v154, v154 quad_perm:[1,0,3,2] row_mask:0xf bank_mask:0xf bound_ctrl:1
	v_pk_mul_f32 v[144:145], v[148:149], v[136:137]
	v_add_f32_e32 v162, v152, v153
	v_add_f32_dpp v154, v154, v154 quad_perm:[2,3,0,1] row_mask:0xf bank_mask:0xf bound_ctrl:1
	v_pk_fma_f32 v[142:143], v[242:243], v[132:133], v[142:143] op_sel:[1,0,0] op_sel_hi:[1,1,1]
	v_pk_fma_f32 v[144:145], v[242:243], v[224:225], v[144:145] op_sel:[1,0,0] op_sel_hi:[1,1,1]
	v_add_f32_dpp v154, v154, v154 row_half_mirror row_mask:0xf bank_mask:0xf bound_ctrl:1
	ds_read_b128 v[206:209], v184 offset:21504
	ds_read_b128 v[210:213], v184 offset:21520
	v_add_f32_dpp v154, v154, v154 row_mirror row_mask:0xf bank_mask:0xf bound_ctrl:1
	ds_read_b64 v[232:233], v184 offset:21536
	v_pk_fma_f32 v[142:143], v[154:155], v[130:131], v[142:143] op_sel_hi:[0,1,1]
	v_pk_fma_f32 v[144:145], v[154:155], v[222:223], v[144:145] op_sel_hi:[0,1,1]
	ds_read_b128 v[214:217], v185 offset:21504
	ds_read_b128 v[218:221], v185 offset:21520
	ds_read_b64 v[234:235], v185 offset:21536
	s_waitcnt lgkmcnt(6)
	v_pk_mul_f32 v[150:151], v[142:143], v[190:191]
	v_pk_fma_f32 v[150:151], v[144:145], v[198:199], v[150:151]
	v_pk_mul_f32 v[152:153], v[142:143], v[236:237]
	v_add_f32_e32 v154, v150, v151
	v_pk_fma_f32 v[152:153], v[144:145], v[238:239], v[152:153]
	v_pk_mul_f32 v[146:147], v[142:143], v[192:193]
	v_add_f32_dpp v154, v154, v154 quad_perm:[1,0,3,2] row_mask:0xf bank_mask:0xf bound_ctrl:1
	v_pk_mul_f32 v[148:149], v[144:145], v[200:201]
	v_add_f32_e32 v163, v152, v153
	v_add_f32_dpp v154, v154, v154 quad_perm:[2,3,0,1] row_mask:0xf bank_mask:0xf bound_ctrl:1
	v_pk_fma_f32 v[146:147], v[240:241], v[196:197], v[146:147] op_sel:[0,0,0] op_sel_hi:[0,1,1]
	v_pk_fma_f32 v[148:149], v[240:241], v[204:205], v[148:149] op_sel:[0,0,0] op_sel_hi:[0,1,1]
	v_add_f32_dpp v154, v154, v154 row_half_mirror row_mask:0xf bank_mask:0xf bound_ctrl:1
	ds_read_b128 v[126:129], v184 offset:23040
	ds_read_b128 v[130:133], v184 offset:23056
	v_add_f32_dpp v154, v154, v154 row_mirror row_mask:0xf bank_mask:0xf bound_ctrl:1
	ds_read_b64 v[236:237], v184 offset:23072
	ds_read_b128 v[134:137], v185 offset:23040
	v_pk_fma_f32 v[146:147], v[154:155], v[194:195], v[146:147] op_sel_hi:[0,1,1]
	v_pk_fma_f32 v[148:149], v[154:155], v[202:203], v[148:149] op_sel_hi:[0,1,1]
	ds_read_b128 v[222:225], v185 offset:23056
	ds_read_b64 v[238:239], v185 offset:23072
	ds_read2_b32 v[242:243], v227 offset0:160 offset1:176
	s_waitcnt lgkmcnt(7)
	v_pk_mul_f32 v[150:151], v[146:147], v[206:207]
	v_pk_fma_f32 v[150:151], v[148:149], v[214:215], v[150:151]
	v_pk_mul_f32 v[152:153], v[146:147], v[228:229]
	v_add_f32_e32 v154, v150, v151
	v_pk_fma_f32 v[152:153], v[148:149], v[230:231], v[152:153]
	v_pk_mul_f32 v[142:143], v[146:147], v[208:209]
	v_add_f32_dpp v154, v154, v154 quad_perm:[1,0,3,2] row_mask:0xf bank_mask:0xf bound_ctrl:1
	v_pk_mul_f32 v[144:145], v[148:149], v[216:217]
	v_add_f32_e32 v164, v152, v153
	v_add_f32_dpp v154, v154, v154 quad_perm:[2,3,0,1] row_mask:0xf bank_mask:0xf bound_ctrl:1
	v_pk_fma_f32 v[142:143], v[240:241], v[212:213], v[142:143] op_sel:[1,0,0] op_sel_hi:[1,1,1]
	v_pk_fma_f32 v[144:145], v[240:241], v[220:221], v[144:145] op_sel:[1,0,0] op_sel_hi:[1,1,1]
	v_add_f32_dpp v154, v154, v154 row_half_mirror row_mask:0xf bank_mask:0xf bound_ctrl:1
	ds_read_b128 v[190:193], v184 offset:24576
	ds_read_b128 v[194:197], v184 offset:24592
	v_add_f32_dpp v154, v154, v154 row_mirror row_mask:0xf bank_mask:0xf bound_ctrl:1
	ds_read_b64 v[228:229], v184 offset:24608
	v_pk_fma_f32 v[142:143], v[154:155], v[210:211], v[142:143] op_sel_hi:[0,1,1]
	v_pk_fma_f32 v[144:145], v[154:155], v[218:219], v[144:145] op_sel_hi:[0,1,1]
	ds_read_b128 v[198:201], v185 offset:24576
	ds_read_b128 v[202:205], v185 offset:24592
	ds_read_b64 v[230:231], v185 offset:24608
	s_waitcnt lgkmcnt(6)
; __device__ __forceinline__ void wkv_phase(const WkvT& W, unsigned char* lds) {
;     ...
;                 for (int t = 0; t < 32; ++t) {
;                     const f32x2 a2 = {nA[0], nA[1]}, w2 = {nA[2], nA[3]}, b2 = {nB[0], nB[1]}, k2 = {nB[2], nB[3]}, r2 = nr; const float v = nv;
;                     if (t + 1 < 32) { nA = *(const f32x4*)(pp + (t + 1) * 384); nB = *(const f32x4*)(pp + (t + 1) * 384 + 4); nr = *(const f32x2*)(pp + (t + 1) * 384 + 8); nv = pv[(t + 1) * 16]; }
;                     float S0 = S.x, S1 = S.y;
;                     float d = S0 * a2.x; d = __builtin_fmaf(S1, a2.y, d);
;                     float t0 = S0 * w2.x; t0 = __builtin_fmaf(v, k2.x, t0); asm volatile("" : "+v"(t0));
;                     float t1 = S1 * w2.y; t1 = __builtin_fmaf(v, k2.y, t1); asm volatile("" : "+v"(t1));
;                     float yprev; const float sa = wkv_reduce(d, ep, yprev);
;                     S0 = __builtin_fmaf(sa, b2.x, t0); asm volatile("" : "+v"(S0));
;                     S1 = __builtin_fmaf(sa, b2.y, t1); asm volatile("" : "+v"(S1));
;                     ep = S0 * r2.x; ep = __builtin_fmaf(S1, r2.y, ep);
;                     S.x = S0; S.y = S1;
	v_pk_mul_f32 v[150:151], v[142:143], v[126:127]
	v_pk_fma_f32 v[150:151], v[144:145], v[134:135], v[150:151]
	v_pk_mul_f32 v[152:153], v[142:143], v[232:233]
	v_add_f32_e32 v154, v150, v151
	v_pk_fma_f32 v[152:153], v[144:145], v[234:235], v[152:153]
	v_pk_mul_f32 v[146:147], v[142:143], v[128:129]
	v_add_f32_dpp v154, v154, v154 quad_perm:[1,0,3,2] row_mask:0xf bank_mask:0xf bound_ctrl:1
	v_pk_mul_f32 v[148:149], v[144:145], v[136:137]
	v_add_f32_e32 v165, v152, v153
	v_add_f32_dpp v154, v154, v154 quad_perm:[2,3,0,1] row_mask:0xf bank_mask:0xf bound_ctrl:1
	v_pk_fma_f32 v[146:147], v[242:243], v[132:133], v[146:147] op_sel:[0,0,0] op_sel_hi:[0,1,1]
	v_pk_fma_f32 v[148:149], v[242:243], v[224:225], v[148:149] op_sel:[0,0,0] op_sel_hi:[0,1,1]
	v_add_f32_dpp v154, v154, v154 row_half_mirror row_mask:0xf bank_mask:0xf bound_ctrl:1
	ds_read_b128 v[206:209], v184 offset:26112
	ds_read_b128 v[210:213], v184 offset:26128
	v_add_f32_dpp v154, v154, v154 row_mirror row_mask:0xf bank_mask:0xf bound_ctrl:1
	ds_read_b64 v[232:233], v184 offset:26144
	ds_read_b128 v[214:217], v185 offset:26112
	v_pk_fma_f32 v[146:147], v[154:155], v[130:131], v[146:147] op_sel_hi:[0,1,1]
	v_pk_fma_f32 v[148:149], v[154:155], v[222:223], v[148:149] op_sel_hi:[0,1,1]
	ds_read_b128 v[218:221], v185 offset:26128
	ds_read_b64 v[234:235], v185 offset:26144
	ds_read2_b32 v[240:241], v227 offset0:192 offset1:208
	s_waitcnt lgkmcnt(7)
	v_pk_mul_f32 v[150:151], v[146:147], v[190:191]
	v_pk_fma_f32 v[150:151], v[148:149], v[198:199], v[150:151]
	v_pk_mul_f32 v[152:153], v[146:147], v[236:237]
	v_add_f32_e32 v154, v150, v151
	v_pk_fma_f32 v[152:153], v[148:149], v[238:239], v[152:153]
	v_pk_mul_f32 v[142:143], v[146:147], v[192:193]
	v_add_f32_dpp v154, v154, v154 quad_perm:[1,0,3,2] row_mask:0xf bank_mask:0xf bound_ctrl:1
	v_pk_mul_f32 v[144:145], v[148:149], v[200:201]
	v_add_f32_e32 v166, v152, v153
	v_add_f32_dpp v154, v154, v154 quad_perm:[2,3,0,1] row_mask:0xf bank_mask:0xf bound_ctrl:1
	v_pk_fma_f32 v[142:143], v[242:243], v[196:197], v[142:143] op_sel:[1,0,0] op_sel_hi:[1,1,1]
	v_pk_fma_f32 v[144:145], v[242:243], v[204:205], v[144:145] op_sel:[1,0,0] op_sel_hi:[1,1,1]
	v_add_f32_dpp v154, v154, v154 row_half_mirror row_mask:0xf bank_mask:0xf bound_ctrl:1
	ds_read_b128 v[126:129], v184 offset:27648
	ds_read_b128 v[130:133], v184 offset:27664
	v_add_f32_dpp v154, v154, v154 row_mirror row_mask:0xf bank_mask:0xf bound_ctrl:1
	ds_read_b64 v[236:237], v184 offset:27680
	v_pk_fma_f32 v[142:143], v[154:155], v[194:195], v[142:143] op_sel_hi:[0,1,1]
	v_pk_fma_f32 v[144:145], v[154:155], v[202:203], v[144:145] op_sel_hi:[0,1,1]
	ds_read_b128 v[134:137], v185 offset:27648
	ds_read_b128 v[222:225], v185 offset:27664
	ds_read_b64 v[238:239], v185 offset:27680
	s_waitcnt lgkmcnt(6)
	v_pk_mul_f32 v[150:151], v[142:143], v[206:207]
	v_pk_fma_f32 v[150:151], v[144:145], v[214:215], v[150:151]
	v_pk_mul_f32 v[152:153], v[142:143], v[228:229]
	v_add_f32_e32 v154, v150, v151
	v_pk_fma_f32 v[152:153], v[144:145], v[230:231], v[152:153]
	v_pk_mul_f32 v[146:147], v[142:143], v[208:209]
	v_add_f32_dpp v154, v154, v154 quad_perm:[1,0,3,2] row_mask:0xf bank_mask:0xf bound_ctrl:1
	v_pk_mul_f32 v[148:149], v[144:145], v[216:217]
	v_add_f32_e32 v167, v152, v153
	v_add_f32_dpp v154, v154, v154 quad_perm:[2,3,0,1] row_mask:0xf bank_mask:0xf bound_ctrl:1
	v_pk_fma_f32 v[146:147], v[240:241], v[212:213], v[146:147] op_sel:[0,0,0] op_sel_hi:[0,1,1]
	v_pk_fma_f32 v[148:149], v[240:241], v[220:221], v[148:149] op_sel:[0,0,0] op_sel_hi:[0,1,1]
	v_add_f32_dpp v154, v154, v154 row_half_mirror row_mask:0xf bank_mask:0xf bound_ctrl:1
	ds_read_b128 v[190:193], v184 offset:29184
	ds_read_b128 v[194:197], v184 offset:29200
	v_add_f32_dpp v154, v154, v154 row_mirror row_mask:0xf bank_mask:0xf bound_ctrl:1
	ds_read_b64 v[228:229], v184 offset:29216
	ds_read_b128 v[198:201], v185 offset:29184
	v_pk_fma_f32 v[146:147], v[154:155], v[210:211], v[146:147] op_sel_hi:[0,1,1]
	v_pk_fma_f32 v[148:149], v[154:155], v[218:219], v[148:149] op_sel_hi:[0,1,1]
	ds_read_b128 v[202:205], v185 offset:29200
	ds_read_b64 v[230:231], v185 offset:29216
	ds_read2_b32 v[242:243], v227 offset0:224 offset1:240
	s_waitcnt lgkmcnt(7)
	v_pk_mul_f32 v[150:151], v[146:147], v[126:127]
	v_pk_fma_f32 v[150:151], v[148:149], v[134:135], v[150:151]
	v_pk_mul_f32 v[152:153], v[146:147], v[232:233]
	v_add_f32_e32 v154, v150, v151
	v_pk_fma_f32 v[152:153], v[148:149], v[234:235], v[152:153]
	v_pk_mul_f32 v[142:143], v[146:147], v[128:129]
	v_add_f32_dpp v154, v154, v154 quad_perm:[1,0,3,2] row_mask:0xf bank_mask:0xf bound_ctrl:1
	v_pk_mul_f32 v[144:145], v[148:149], v[136:137]
	v_add_f32_e32 v168, v152, v153
	v_add_f32_dpp v154, v154, v154 quad_perm:[2,3,0,1] row_mask:0xf bank_mask:0xf bound_ctrl:1
	v_pk_fma_f32 v[142:143], v[240:241], v[132:133], v[142:143] op_sel:[1,0,0] op_sel_hi:[1,1,1]
	v_pk_fma_f32 v[144:145], v[240:241], v[224:225], v[144:145] op_sel:[1,0,0] op_sel_hi:[1,1,1]
	v_add_f32_dpp v154, v154, v154 row_half_mirror row_mask:0xf bank_mask:0xf bound_ctrl:1
	ds_read_b128 v[206:209], v184 offset:30720
	ds_read_b128 v[210:213], v184 offset:30736
	v_add_f32_dpp v154, v154, v154 row_mirror row_mask:0xf bank_mask:0xf bound_ctrl:1
	ds_read_b64 v[232:233], v184 offset:30752
	v_pk_fma_f32 v[142:143], v[154:155], v[130:131], v[142:143] op_sel_hi:[0,1,1]
	v_pk_fma_f32 v[144:145], v[154:155], v[222:223], v[144:145] op_sel_hi:[0,1,1]
	ds_read_b128 v[214:217], v185 offset:30720
	ds_read_b128 v[218:221], v185 offset:30736
	ds_read_b64 v[234:235], v185 offset:30752
	s_waitcnt lgkmcnt(6)
; __device__ __forceinline__ void wkv_phase(const WkvT& W, unsigned char* lds) {
;     ...
;                 for (int t = 0; t < 32; ++t) {
;                     const f32x2 a2 = {nA[0], nA[1]}, w2 = {nA[2], nA[3]}, b2 = {nB[0], nB[1]}, k2 = {nB[2], nB[3]}, r2 = nr; const float v = nv;
;                     if (t + 1 < 32) { nA = *(const f32x4*)(pp + (t + 1) * 384); nB = *(const f32x4*)(pp + (t + 1) * 384 + 4); nr = *(const f32x2*)(pp + (t + 1) * 384 + 8); nv = pv[(t + 1) * 16]; }
;                     float S0 = S.x, S1 = S.y;
;                     float d = S0 * a2.x; d = __builtin_fmaf(S1, a2.y, d);
;                     float t0 = S0 * w2.x; t0 = __builtin_fmaf(v, k2.x, t0); asm volatile("" : "+v"(t0));
;                     float t1 = S1 * w2.y; t1 = __builtin_fmaf(v, k2.y, t1); asm volatile("" : "+v"(t1));
;                     float yprev; const float sa = wkv_reduce(d, ep, yprev);
;                     S0 = __builtin_fmaf(sa, b2.x, t0); asm volatile("" : "+v"(S0));
;                     S1 = __builtin_fmaf(sa, b2.y, t1); asm volatile("" : "+v"(S1));
;                     ep = S0 * r2.x; ep = __builtin_fmaf(S1, r2.y, ep);
;                     S.x = S0; S.y = S1;
;                     if (t >= 1) { const bool hit = oddrow && ((lane & 15) == ((t - 1) & 15)); if (t <= 16) yk0 = hit ? yprev : yk0; else yk1 = hit ? yprev : yk1; }
;                 }
;                 { float ylast; (void)wkv_reduce(0.f, ep, ylast); yk1 = (oddrow && (lane & 15) == 15) ? ylast : yk1; }
;                 if (oddrow) { sY[bi * 512 + (lane & 15) * 16 + il] = yk0; sY[bi * 512 + (16 + (lane & 15)) * 16 + il] = yk1; }
	v_pk_mul_f32 v[150:151], v[142:143], v[190:191]
	v_pk_fma_f32 v[150:151], v[144:145], v[198:199], v[150:151]
	v_pk_mul_f32 v[152:153], v[142:143], v[236:237]
	v_add_f32_e32 v154, v150, v151
	v_pk_fma_f32 v[152:153], v[144:145], v[238:239], v[152:153]
	v_pk_mul_f32 v[146:147], v[142:143], v[192:193]
	v_add_f32_dpp v154, v154, v154 quad_perm:[1,0,3,2] row_mask:0xf bank_mask:0xf bound_ctrl:1
	v_pk_mul_f32 v[148:149], v[144:145], v[200:201]
	v_add_f32_e32 v169, v152, v153
	v_add_f32_dpp v154, v154, v154 quad_perm:[2,3,0,1] row_mask:0xf bank_mask:0xf bound_ctrl:1
	v_pk_fma_f32 v[146:147], v[242:243], v[196:197], v[146:147] op_sel:[0,0,0] op_sel_hi:[0,1,1]
	v_pk_fma_f32 v[148:149], v[242:243], v[204:205], v[148:149] op_sel:[0,0,0] op_sel_hi:[0,1,1]
	v_add_f32_dpp v154, v154, v154 row_half_mirror row_mask:0xf bank_mask:0xf bound_ctrl:1
	s_nop 1
	v_add_f32_dpp v154, v154, v154 row_mirror row_mask:0xf bank_mask:0xf bound_ctrl:1
	v_pk_fma_f32 v[146:147], v[154:155], v[194:195], v[146:147] op_sel_hi:[0,1,1]
	v_pk_fma_f32 v[148:149], v[154:155], v[202:203], v[148:149] op_sel_hi:[0,1,1]
	s_waitcnt lgkmcnt(0)
	v_pk_mul_f32 v[150:151], v[146:147], v[206:207]
	v_pk_fma_f32 v[150:151], v[148:149], v[214:215], v[150:151]
	v_pk_mul_f32 v[152:153], v[146:147], v[228:229]
	v_add_f32_e32 v154, v150, v151
	v_pk_fma_f32 v[152:153], v[148:149], v[230:231], v[152:153]
	v_pk_mul_f32 v[142:143], v[146:147], v[208:209]
	v_add_f32_dpp v154, v154, v154 quad_perm:[1,0,3,2] row_mask:0xf bank_mask:0xf bound_ctrl:1
	v_pk_mul_f32 v[144:145], v[148:149], v[216:217]
	v_add_f32_e32 v170, v152, v153
	v_add_f32_dpp v154, v154, v154 quad_perm:[2,3,0,1] row_mask:0xf bank_mask:0xf bound_ctrl:1
	v_pk_fma_f32 v[142:143], v[242:243], v[212:213], v[142:143] op_sel:[1,0,0] op_sel_hi:[1,1,1]
	v_pk_fma_f32 v[144:145], v[242:243], v[220:221], v[144:145] op_sel:[1,0,0] op_sel_hi:[1,1,1]
	v_add_f32_dpp v154, v154, v154 row_half_mirror row_mask:0xf bank_mask:0xf bound_ctrl:1
	s_nop 1
	v_add_f32_dpp v154, v154, v154 row_mirror row_mask:0xf bank_mask:0xf bound_ctrl:1
	v_pk_fma_f32 v[142:143], v[154:155], v[210:211], v[142:143] op_sel_hi:[0,1,1]
	v_pk_fma_f32 v[144:145], v[154:155], v[218:219], v[144:145] op_sel_hi:[0,1,1]
	v_pk_mul_f32 v[152:153], v[142:143], v[232:233]
	v_pk_fma_f32 v[152:153], v[144:145], v[234:235], v[152:153]
	s_nop 0
	v_add_f32_e32 v171, v152, v153
	v_add_f32_dpp v172, v156, v156 row_ror:8 row_mask:0xf bank_mask:0x3
	v_add_f32_dpp v173, v157, v157 row_ror:8 row_mask:0xf bank_mask:0x3
	v_add_f32_dpp v174, v158, v158 row_ror:8 row_mask:0xf bank_mask:0x3
	v_add_f32_dpp v175, v159, v159 row_ror:8 row_mask:0xf bank_mask:0x3
	v_add_f32_dpp v176, v160, v160 row_ror:8 row_mask:0xf bank_mask:0x3
	v_add_f32_dpp v177, v161, v161 row_ror:8 row_mask:0xf bank_mask:0x3
	v_add_f32_dpp v178, v162, v162 row_ror:8 row_mask:0xf bank_mask:0x3
	v_add_f32_dpp v179, v163, v163 row_ror:8 row_mask:0xf bank_mask:0x3
	v_add_f32_dpp v172, v164, v164 row_ror:8 row_mask:0xf bank_mask:0xc
	v_add_f32_dpp v173, v165, v165 row_ror:8 row_mask:0xf bank_mask:0xc
	v_add_f32_dpp v174, v166, v166 row_ror:8 row_mask:0xf bank_mask:0xc
	v_add_f32_dpp v175, v167, v167 row_ror:8 row_mask:0xf bank_mask:0xc
	v_add_f32_dpp v176, v168, v168 row_ror:8 row_mask:0xf bank_mask:0xc
	v_add_f32_dpp v177, v169, v169 row_ror:8 row_mask:0xf bank_mask:0xc
	v_add_f32_dpp v178, v170, v170 row_ror:8 row_mask:0xf bank_mask:0xc
	v_add_f32_dpp v179, v171, v171 row_ror:8 row_mask:0xf bank_mask:0xc
	v_add_f32_dpp v156, v172, v172 row_half_mirror row_mask:0xf bank_mask:0x5
	v_add_f32_dpp v157, v173, v173 row_half_mirror row_mask:0xf bank_mask:0x5
	v_add_f32_dpp v158, v174, v174 row_half_mirror row_mask:0xf bank_mask:0x5
	v_add_f32_dpp v159, v175, v175 row_half_mirror row_mask:0xf bank_mask:0x5
	v_add_f32_dpp v156, v176, v176 row_half_mirror row_mask:0xf bank_mask:0xa
	v_add_f32_dpp v157, v177, v177 row_half_mirror row_mask:0xf bank_mask:0xa
	v_add_f32_dpp v158, v178, v178 row_half_mirror row_mask:0xf bank_mask:0xa
	v_add_f32_dpp v159, v179, v179 row_half_mirror row_mask:0xf bank_mask:0xa
	v_cndmask_b32_e64 v178, v156, v158, s[14:15]
	v_cndmask_b32_e64 v176, v158, v156, s[14:15]
	v_cndmask_b32_e64 v179, v157, v159, s[14:15]
	v_cndmask_b32_e64 v177, v159, v157, s[14:15]
	s_nop 1
	v_add_f32_dpp v172, v176, v178 quad_perm:[2,3,0,1] row_mask:0xf bank_mask:0xf
	v_add_f32_dpp v173, v177, v179 quad_perm:[2,3,0,1] row_mask:0xf bank_mask:0xf
	v_cndmask_b32_e64 v176, v173, v172, s[16:17]
	v_cndmask_b32_e64 v178, v172, v173, s[16:17]
	s_nop 1
	v_add_f32_dpp v181, v176, v178 quad_perm:[1,0,3,2] row_mask:0xf bank_mask:0xf
	ds_write2st64_b32 v187, v180, v181 offset0:8 offset1:12
